# scan: next-next chunk's loads requested before the chunk barrier (overlaps LDS write drain); gMLP: gate-half loads requested before the next slice's data loads, counted wait
# speedup vs baseline: 1.0121x; 1.0023x over previous
; #define LAS __attribute__((address_space(3)))
; __device__ __forceinline__ void post_phase(const KAS Args& a, LAS unsigned char* lds, int i, const int tid_, const int bid, const int nblk) {
;     ...
;             u32x2 uz[8];
; #pragma unroll
;             for (int dt = 0; dt < 8; ++dt) uz[dt] = *(const u32x2*)(Z + (m0 + etok) * ZC + 1792 + g * 128 + 16 * dt + 4 * l4);
;             const float bs = a.bsp[(i * 4 + g) * 128 + etok];
;             __syncthreads();
;             f32x4 acc[8];
; #pragma unroll
;             for (int dt = 0; dt < 8; ++dt) acc[dt] = (f32x4){0.f, 0.f, 0.f, 0.f};
; #pragma unroll
;             for (int ks = 0; ks < 4; ++ks) { const bf16x8 wf = *(const LAS bf16x8*)(Wl + (16 * wave + l15) * 136 + 32 * ks + 8 * l4);
; #pragma unroll
;                 for (int dt = 0; dt < 8; ++dt) { const bf16x8 sf = *(const LAS bf16x8*)(St + (16 * dt + l15) * 136 + 32 * ks + 8 * l4);
;                     acc[dt] = __builtin_amdgcn_mfma_f32_16x16x32_bf16(sf, wf, acc[dt], 0, 0, 0); } }
.LBB0_164:
	s_lshl_b32 s92, s3, 1
	s_waitcnt lgkmcnt(0)
	s_barrier
	ds_read_b128 v[52:55], v94 offset:1024
	ds_read_b128 v[56:59], v131 offset:35840
	ds_read_b128 v[60:63], v131 offset:40192
	ds_read_b128 v[64:67], v131 offset:44544
	ds_read_b128 v[68:71], v131 offset:48896
	ds_read_b128 v[72:75], v131 offset:53248
	ds_read_b128 v[76:79], v131 offset:57600
	ds_read_b128 v[80:83], v131 offset:61952
	ds_read_b128 v[134:137], v132 offset:35840
	s_waitcnt lgkmcnt(7)
	v_mfma_f32_16x16x32_bf16 v[56:59], v[56:59], v[52:55], 0
	v_lshl_add_u64 v[124:125], v[106:107], 0, s[92:93]
	s_cmp_eq_u32 s76, 4
	s_mov_b32 s2, s76
	s_waitcnt lgkmcnt(6)
	v_mfma_f32_16x16x32_bf16 v[60:63], v[60:63], v[52:55], 0
	s_waitcnt lgkmcnt(5)
	v_mfma_f32_16x16x32_bf16 v[64:67], v[64:67], v[52:55], 0
	s_waitcnt lgkmcnt(4)
	v_mfma_f32_16x16x32_bf16 v[68:71], v[68:71], v[52:55], 0
	s_waitcnt lgkmcnt(3)
	v_mfma_f32_16x16x32_bf16 v[72:75], v[72:75], v[52:55], 0
	s_waitcnt lgkmcnt(2)
	v_mfma_f32_16x16x32_bf16 v[76:79], v[76:79], v[52:55], 0
	s_waitcnt lgkmcnt(1)
	v_mfma_f32_16x16x32_bf16 v[80:83], v[80:83], v[52:55], 0
	s_waitcnt lgkmcnt(0)
	v_mfma_f32_16x16x32_bf16 v[52:55], v[134:137], v[52:55], 0
	ds_read_b128 v[134:137], v94 offset:1088
	ds_read_b128 v[138:141], v131 offset:35904
	s_waitcnt lgkmcnt(0)
	v_mfma_f32_16x16x32_bf16 v[56:59], v[138:141], v[134:137], v[56:59]
	ds_read_b128 v[138:141], v131 offset:40256
	s_waitcnt lgkmcnt(0)
	v_mfma_f32_16x16x32_bf16 v[60:63], v[138:141], v[134:137], v[60:63]
	ds_read_b128 v[138:141], v131 offset:44608
	s_waitcnt lgkmcnt(0)
	v_mfma_f32_16x16x32_bf16 v[64:67], v[138:141], v[134:137], v[64:67]
	ds_read_b128 v[138:141], v131 offset:48960
	s_waitcnt lgkmcnt(0)
	v_mfma_f32_16x16x32_bf16 v[68:71], v[138:141], v[134:137], v[68:71]
	ds_read_b128 v[138:141], v131 offset:53312
	s_waitcnt lgkmcnt(0)
	v_mfma_f32_16x16x32_bf16 v[72:75], v[138:141], v[134:137], v[72:75]
	ds_read_b128 v[138:141], v131 offset:57664
	s_waitcnt lgkmcnt(0)
	v_mfma_f32_16x16x32_bf16 v[76:79], v[138:141], v[134:137], v[76:79]
	ds_read_b128 v[138:141], v131 offset:62016
	s_waitcnt lgkmcnt(0)
	v_mfma_f32_16x16x32_bf16 v[80:83], v[138:141], v[134:137], v[80:83]
	ds_read_b128 v[138:141], v132 offset:35904
	s_waitcnt lgkmcnt(0)
	v_mfma_f32_16x16x32_bf16 v[52:55], v[138:141], v[134:137], v[52:55]
	ds_read_b128 v[134:137], v94 offset:1152
	ds_read_b128 v[138:141], v131 offset:35968
	s_waitcnt lgkmcnt(0)
	v_mfma_f32_16x16x32_bf16 v[56:59], v[138:141], v[134:137], v[56:59]
	ds_read_b128 v[138:141], v131 offset:40320
	s_waitcnt lgkmcnt(0)
	v_mfma_f32_16x16x32_bf16 v[60:63], v[138:141], v[134:137], v[60:63]
	ds_read_b128 v[138:141], v131 offset:44672
	s_waitcnt lgkmcnt(0)
	v_mfma_f32_16x16x32_bf16 v[64:67], v[138:141], v[134:137], v[64:67]
	ds_read_b128 v[138:141], v131 offset:49024
	s_waitcnt lgkmcnt(0)
	v_mfma_f32_16x16x32_bf16 v[68:71], v[138:141], v[134:137], v[68:71]
	ds_read_b128 v[138:141], v131 offset:53376
	s_waitcnt lgkmcnt(0)
	v_mfma_f32_16x16x32_bf16 v[138:141], v[138:141], v[134:137], v[72:75]
	s_nop 2
	ds_read_b128 v[72:75], v131 offset:57728
	s_waitcnt lgkmcnt(0)
	v_mfma_f32_16x16x32_bf16 v[142:145], v[72:75], v[134:137], v[76:79]
	ds_read_b128 v[72:75], v131 offset:62080
	s_waitcnt lgkmcnt(0)
	v_mfma_f32_16x16x32_bf16 v[146:149], v[72:75], v[134:137], v[80:83]
	ds_read_b128 v[72:75], v132 offset:35968
	s_waitcnt lgkmcnt(0)
	v_mfma_f32_16x16x32_bf16 v[52:55], v[72:75], v[134:137], v[52:55]
	ds_read_b128 v[134:137], v94 offset:1216
	ds_read_b128 v[72:75], v131 offset:36032
	s_waitcnt lgkmcnt(0)
	v_mfma_f32_16x16x32_bf16 v[80:83], v[72:75], v[134:137], v[56:59]
	s_nop 2
	ds_read_b128 v[56:59], v131 offset:40384
	s_waitcnt lgkmcnt(0)
	v_mfma_f32_16x16x32_bf16 v[76:79], v[56:59], v[134:137], v[60:63]
	ds_read_b128 v[56:59], v131 offset:44736
	s_cmp_eq_u32 s76, 4
	s_cbranch_scc1 .Lgm_last
	s_waitcnt vmcnt(12)
	s_branch .Lgm_go

; __device__ __forceinline__ unsigned pk2(float lo, float hi) { f32x2 v = {lo, hi}; bf16x2_t b = __builtin_convertvector(v, bf16x2_t); return __builtin_bit_cast(unsigned, b); }
; __device__ __forceinline__ float bflo(unsigned w) { return __uint_as_float(w << 16); }
; __device__ __forceinline__ float bfhi(unsigned w) { return __uint_as_float(w & 0xffff0000u); }
; __device__ __forceinline__ void post_phase(const KAS Args& a, LAS unsigned char* lds, int i, const int tid_, const int bid, const int nblk) {
;     ...
; #pragma unroll
;             for (int dt = 0; dt < 8; ++dt) { const f32x2 u0 = {bflo(uz[dt].x), bfhi(uz[dt].x)}, u1 = {bflo(uz[dt].y), bfhi(uz[dt].y)};
;                 *(u32x2*)(Y + (m0 + etok) * D + 512 + g * 128 + 16 * dt + 4 * l4) = (u32x2){pk2(u0.x * (acc[dt][0] + bs), u0.y * (acc[dt][1] + bs)), pk2(u1.x * (acc[dt][2] + bs), u1.y * (acc[dt][3] + bs))}; }
.Lgm_go:
	v_pk_add_f32 v[80:81], v[2:3], v[80:81] op_sel_hi:[0,1]
	v_pk_add_f32 v[82:83], v[2:3], v[82:83] op_sel_hi:[0,1]
	s_waitcnt lgkmcnt(0)
	v_mfma_f32_16x16x32_bf16 v[72:75], v[56:59], v[134:137], v[64:67]
	ds_read_b128 v[56:59], v131 offset:49088
	s_nop 0
	v_pk_add_f32 v[76:77], v[2:3], v[76:77] op_sel_hi:[0,1]
	v_pk_add_f32 v[78:79], v[2:3], v[78:79] op_sel_hi:[0,1]
	s_waitcnt lgkmcnt(0)
	v_mfma_f32_16x16x32_bf16 v[68:71], v[56:59], v[134:137], v[68:71]
	ds_read_b128 v[56:59], v131 offset:53440
	s_nop 0
	v_pk_add_f32 v[72:73], v[2:3], v[72:73] op_sel_hi:[0,1]
	v_pk_add_f32 v[74:75], v[2:3], v[74:75] op_sel_hi:[0,1]
	s_waitcnt lgkmcnt(0)
	v_mfma_f32_16x16x32_bf16 v[64:67], v[56:59], v[134:137], v[138:141]
	ds_read_b128 v[56:59], v131 offset:57792
	s_nop 1
	ds_read_b128 v[138:141], v132 offset:36032
	v_pk_add_f32 v[68:69], v[2:3], v[68:69] op_sel_hi:[0,1]
	s_waitcnt lgkmcnt(1)
	v_mfma_f32_16x16x32_bf16 v[60:63], v[56:59], v[134:137], v[142:145]
	ds_read_b128 v[56:59], v131 offset:62144
	v_pk_add_f32 v[70:71], v[2:3], v[70:71] op_sel_hi:[0,1]
	v_pk_add_f32 v[64:65], v[2:3], v[64:65] op_sel_hi:[0,1]
	s_waitcnt lgkmcnt(0)
	v_mfma_f32_16x16x32_bf16 v[56:59], v[56:59], v[134:137], v[146:149]
	v_add_f32_e64 v66, v2, v66
	v_add_f32_e64 v67, v2, v67
	s_nop 0
	v_pk_add_f32 v[60:61], v[2:3], v[60:61] op_sel_hi:[0,1]
	v_pk_add_f32 v[62:63], v[2:3], v[62:63] op_sel_hi:[0,1]
	v_mfma_f32_16x16x32_bf16 v[52:55], v[138:141], v[134:137], v[52:55]
	v_lshlrev_b32_e32 v134, 16, v122
	v_and_b32_e32 v135, 0xffff0000, v122
	v_lshlrev_b32_e32 v122, 16, v123
	v_and_b32_e32 v123, 0xffff0000, v123
	v_pk_mul_f32 v[80:81], v[80:81], v[134:135]
	v_pk_mul_f32 v[82:83], v[82:83], v[122:123]
	v_cvt_pk_bf16_f32 v80, v80, v81
	v_cvt_pk_bf16_f32 v81, v82, v83
	global_store_dwordx2 v[124:125], v[80:81], off offset:1024
	v_lshlrev_b32_e32 v80, 16, v120
	v_and_b32_e32 v81, 0xffff0000, v120
	v_pk_mul_f32 v[76:77], v[76:77], v[80:81]
	v_lshlrev_b32_e32 v80, 16, v121
	v_and_b32_e32 v81, 0xffff0000, v121
	v_pk_mul_f32 v[78:79], v[78:79], v[80:81]
	v_cvt_pk_bf16_f32 v76, v76, v77
	v_cvt_pk_bf16_f32 v77, v78, v79
	global_store_dwordx2 v[124:125], v[76:77], off offset:1056
	v_lshlrev_b32_e32 v76, 16, v118
	v_and_b32_e32 v77, 0xffff0000, v118
	v_pk_mul_f32 v[72:73], v[72:73], v[76:77]
	v_lshlrev_b32_e32 v76, 16, v119
	v_and_b32_e32 v77, 0xffff0000, v119
	v_pk_mul_f32 v[74:75], v[74:75], v[76:77]
	v_cvt_pk_bf16_f32 v72, v72, v73
	v_cvt_pk_bf16_f32 v73, v74, v75
	global_store_dwordx2 v[124:125], v[72:73], off offset:1088
	v_lshlrev_b32_e32 v72, 16, v116
	v_and_b32_e32 v73, 0xffff0000, v116
	v_pk_mul_f32 v[68:69], v[68:69], v[72:73]
	v_lshlrev_b32_e32 v72, 16, v117
	v_and_b32_e32 v73, 0xffff0000, v117
	v_pk_mul_f32 v[70:71], v[70:71], v[72:73]
	v_cvt_pk_bf16_f32 v68, v68, v69
	v_cvt_pk_bf16_f32 v69, v70, v71
	global_store_dwordx2 v[124:125], v[68:69], off offset:1120
	v_lshlrev_b32_e32 v68, 16, v114
	v_and_b32_e32 v69, 0xffff0000, v114
	v_pk_mul_f32 v[64:65], v[64:65], v[68:69]
	v_lshlrev_b32_e32 v68, 16, v115
	v_and_b32_e32 v69, 0xffff0000, v115
	v_pk_mul_f32 v[66:67], v[66:67], v[68:69]
	v_cvt_pk_bf16_f32 v64, v64, v65
	v_cvt_pk_bf16_f32 v65, v66, v67
	global_store_dwordx2 v[124:125], v[64:65], off offset:1152
	v_lshlrev_b32_e32 v64, 16, v112
	v_and_b32_e32 v65, 0xffff0000, v112
	v_pk_mul_f32 v[60:61], v[60:61], v[64:65]
	v_lshlrev_b32_e32 v64, 16, v113
	v_and_b32_e32 v65, 0xffff0000, v113
	v_pk_mul_f32 v[62:63], v[62:63], v[64:65]
	v_cvt_pk_bf16_f32 v60, v60, v61
	v_cvt_pk_bf16_f32 v61, v62, v63
	global_store_dwordx2 v[124:125], v[60:61], off offset:1184
	v_lshlrev_b32_e32 v60, 16, v110
	v_and_b32_e32 v61, 0xffff0000, v110
	v_pk_add_f32 v[56:57], v[2:3], v[56:57] op_sel_hi:[0,1]
	v_pk_mul_f32 v[56:57], v[56:57], v[60:61]
	v_lshlrev_b32_e32 v60, 16, v111
	v_and_b32_e32 v61, 0xffff0000, v111
	v_pk_add_f32 v[58:59], v[2:3], v[58:59] op_sel_hi:[0,1]
	v_pk_mul_f32 v[58:59], v[58:59], v[60:61]
	v_cvt_pk_bf16_f32 v56, v56, v57
	v_cvt_pk_bf16_f32 v57, v58, v59
	global_store_dwordx2 v[124:125], v[56:57], off offset:1216
	v_lshlrev_b32_e32 v56, 16, v108
	v_and_b32_e32 v57, 0xffff0000, v108
	v_pk_add_f32 v[52:53], v[2:3], v[52:53] op_sel_hi:[0,1]
	v_pk_mul_f32 v[52:53], v[52:53], v[56:57]
	v_lshlrev_b32_e32 v56, 16, v109
	v_and_b32_e32 v57, 0xffff0000, v109
	v_pk_add_f32 v[54:55], v[2:3], v[54:55] op_sel_hi:[0,1]
	v_pk_mul_f32 v[54:55], v[54:55], v[56:57]
	v_cvt_pk_bf16_f32 v52, v52, v53
	v_cvt_pk_bf16_f32 v53, v54, v55
	global_store_dwordx2 v[124:125], v[52:53], off offset:1248
	s_cbranch_scc1 .LBB0_152
; __device__ __forceinline__ unsigned pk2(float lo, float hi) { f32x2 v = {lo, hi}; bf16x2_t b = __builtin_convertvector(v, bf16x2_t); return __builtin_bit_cast(unsigned, b); }
; #define LAS __attribute__((address_space(3)))
; __device__ __forceinline__ void unpack8(const u32x4 w, float (&f)[8]) { f[0] = bflo(w.x); f[1] = bfhi(w.x); f[2] = bflo(w.y); f[3] = bfhi(w.y); f[4] = bflo(w.z); f[5] = bfhi(w.z); f[6] = bflo(w.w); f[7] = bfhi(w.w); }
; __device__ __forceinline__ u32x4 pack8(const float (&f)[8]) { return (u32x4){pk2(f[0], f[1]), pk2(f[2], f[3]), pk2(f[4], f[5]), pk2(f[6], f[7])}; }
; __device__ __forceinline__ void post_phase(const KAS Args& a, LAS unsigned char* lds, int i, const int tid_, const int bid, const int nblk) {
;     ...
;             __syncthreads();
;             { const float mean = stat[2 * stok], rstd = stat[2 * stok + 1];
; #pragma unroll
;               for (int q = 0; q < 4; ++q) { float sv[8], wv[8]; const int d0 = 32 * spart + 8 * q;
;                   unpack8(raw[q], sv);
; #pragma unroll
;                   for (int e = 0; e < 8; ++e) { const int dd = g * 128 + d0 + e; const float sn = (sv[e] - mean) * rstd * a.lng[i * 512 + dd] + a.lnb[i * 512 + dd];
;                       St[(d0 + e) * 136 + stok] = (bf16_t)(pk2(sn, 0.f) & 0xffffu); }
; #pragma unroll
;                   for (int e = 0; e < 4; ++e) { wv[e] = (d0 + e <= stok) ? wr0[q][e] : 0.f; wv[4 + e] = (d0 + 4 + e <= stok) ? wr1[q][e] : 0.f; }
;                   *(LAS u32x4*)(Wl + stok * 136 + d0) = pack8(wv); } }
.LBB0_165:
	s_barrier
	ds_read2_b32 v[108:109], v90 offset1:1
	s_lshl_b32 s3, s2, 7
	s_add_i32 s76, s3, s95
	v_or_b32_e32 v2, s76, v86
	s_waitcnt vmcnt(11)
	v_lshlrev_b32_e32 v52, 16, v12
	v_lshlrev_b64 v[56:57], 2, v[2:3]
	s_waitcnt lgkmcnt(0)
	v_sub_f32_e32 v52, v52, v108
	v_lshl_add_u64 v[58:59], s[80:81], 0, v[56:57]
	v_lshl_add_u64 v[80:81], s[82:83], 0, v[56:57]
	v_lshl_add_u64 v[192:193], s[80:81], 0, v[56:57]
	v_lshl_add_u64 v[194:195], s[82:83], 0, v[56:57]
	v_mul_f32_e32 v117, v109, v52
	global_load_dwordx4 v[52:55], v[58:59], off offset:48
	global_load_dwordx4 v[60:63], v[58:59], off offset:32
	global_load_dwordx4 v[68:71], v[58:59], off offset:16
	global_load_dwordx4 v[72:75], v[58:59], off
	s_nop 0
	global_load_dwordx4 v[56:59], v[80:81], off offset:48
	global_load_dwordx4 v[64:67], v[80:81], off offset:32
	global_load_dwordx4 v[76:79], v[80:81], off offset:16
	s_nop 0
	global_load_dwordx4 v[80:83], v[80:81], off
	global_load_dwordx4 v[150:153], v[192:193], off offset:112
	global_load_dwordx4 v[154:157], v[192:193], off offset:96
	global_load_dwordx4 v[158:161], v[192:193], off offset:80
	global_load_dwordx4 v[162:165], v[192:193], off offset:64
	global_load_dwordx4 v[166:169], v[194:195], off offset:112
	global_load_dwordx4 v[170:173], v[194:195], off offset:96
	global_load_dwordx4 v[174:177], v[194:195], off offset:80
	global_load_dwordx4 v[188:191], v[194:195], off offset:64
	v_and_b32_e32 v110, 0xffff0000, v12
	v_lshlrev_b32_e32 v111, 16, v13
	v_and_b32_e32 v112, 0xffff0000, v13
	v_lshlrev_b32_e32 v113, 16, v14
	v_and_b32_e32 v114, 0xffff0000, v14
	v_lshlrev_b32_e32 v115, 16, v15
	v_and_b32_e32 v116, 0xffff0000, v15
	s_cmp_eq_u32 s2, 3
	s_waitcnt vmcnt(8)
	v_fma_f32 v2, v117, v72, v80
	v_cvt_pk_bf16_f32 v2, v2, s0
	ds_write_b16 v130, v2 offset:35840
	v_sub_f32_e32 v2, v110, v108
	v_mul_f32_e32 v2, v109, v2
	v_fma_f32 v2, v2, v73, v81
	v_cvt_pk_bf16_f32 v2, v2, s0
	ds_write_b16 v130, v2 offset:36112
	v_sub_f32_e32 v2, v111, v108
	v_mul_f32_e32 v2, v109, v2
	v_fma_f32 v2, v2, v74, v82
	v_cvt_pk_bf16_f32 v2, v2, s0
	ds_write_b16 v130, v2 offset:36384
	v_sub_f32_e32 v2, v112, v108
	v_mul_f32_e32 v2, v109, v2
	v_fmac_f32_e32 v83, v2, v75
	v_cvt_pk_bf16_f32 v2, v83, s0
	ds_write_b16 v130, v2 offset:36656
	v_sub_f32_e32 v2, v113, v108
	v_mul_f32_e32 v2, v109, v2
	v_fma_f32 v2, v2, v68, v76
	v_cvt_pk_bf16_f32 v2, v2, s0
	ds_write_b16 v130, v2 offset:36928
	v_sub_f32_e32 v2, v114, v108
	v_mul_f32_e32 v2, v109, v2
	v_fma_f32 v2, v2, v69, v77
	v_cvt_pk_bf16_f32 v2, v2, s0
	ds_write_b16 v130, v2 offset:37200
	v_sub_f32_e32 v2, v115, v108
	v_mul_f32_e32 v2, v109, v2
	v_fma_f32 v2, v2, v70, v78
	v_cvt_pk_bf16_f32 v2, v2, s0
	ds_write_b16 v130, v2 offset:37472
	v_sub_f32_e32 v2, v116, v108
	v_mul_f32_e32 v2, v109, v2
	v_fmac_f32_e32 v79, v2, v71
	v_cvt_pk_bf16_f32 v2, v79, s0
	ds_write_b16 v130, v2 offset:37744
	v_cndmask_b32_e64 v2, v32, 0, s[8:9]
	v_cndmask_b32_e64 v68, 0, v33, s[12:13]
	v_cvt_pk_bf16_f32 v68, v2, v68
	v_lshlrev_b32_e32 v2, 16, v16
	v_cndmask_b32_e64 v70, v28, 0, s[10:11]
	v_cndmask_b32_e64 v71, v29, 0, s[14:15]
	v_cndmask_b32_e64 v69, v34, 0, s[16:17]
	v_cndmask_b32_e64 v72, v30, 0, s[18:19]
	v_cndmask_b32_e64 v73, v35, 0, s[20:21]
	v_cndmask_b32_e64 v74, v31, 0, s[22:23]
	v_sub_f32_e32 v2, v2, v108
	v_cvt_pk_bf16_f32 v69, v69, v73
	v_cvt_pk_bf16_f32 v70, v70, v71
	v_cvt_pk_bf16_f32 v71, v72, v74
	v_mul_f32_e32 v79, v109, v2
	v_add_u32_e32 v2, s76, v86
	ds_write_b128 v95, v[68:71] offset:1024
	v_lshlrev_b64 v[70:71], 2, v[2:3]
	v_fma_f32 v2, v79, v60, v64
	v_and_b32_e32 v72, 0xffff0000, v16
	v_cvt_pk_bf16_f32 v2, v2, s0
	ds_write_b16 v130, v2 offset:38016
	v_sub_f32_e32 v2, v72, v108
	v_mul_f32_e32 v2, v109, v2
	v_fma_f32 v2, v2, v61, v65
	v_lshlrev_b32_e32 v73, 16, v17
	v_cvt_pk_bf16_f32 v2, v2, s0
	ds_write_b16 v130, v2 offset:38288
	v_sub_f32_e32 v2, v73, v108
	v_mul_f32_e32 v2, v109, v2
	v_fma_f32 v2, v2, v62, v66
	v_and_b32_e32 v74, 0xffff0000, v17
	v_cvt_pk_bf16_f32 v2, v2, s0
	ds_write_b16 v130, v2 offset:38560
	v_sub_f32_e32 v2, v74, v108
	v_mul_f32_e32 v2, v109, v2
	v_fmac_f32_e32 v67, v2, v63
	v_lshlrev_b32_e32 v75, 16, v18
	v_cvt_pk_bf16_f32 v2, v67, s0
	ds_write_b16 v130, v2 offset:38832
	v_sub_f32_e32 v2, v75, v108
	v_mul_f32_e32 v2, v109, v2
	v_fma_f32 v2, v2, v52, v56
	v_and_b32_e32 v76, 0xffff0000, v18
	v_cvt_pk_bf16_f32 v2, v2, s0
	ds_write_b16 v130, v2 offset:39104
	v_sub_f32_e32 v2, v76, v108
	v_mul_f32_e32 v2, v109, v2
	v_fma_f32 v2, v2, v53, v57
	v_lshlrev_b32_e32 v77, 16, v19
	v_cvt_pk_bf16_f32 v2, v2, s0
	ds_write_b16 v130, v2 offset:39376
	v_sub_f32_e32 v2, v77, v108
	v_mul_f32_e32 v2, v109, v2
	v_fma_f32 v2, v2, v54, v58
	v_and_b32_e32 v78, 0xffff0000, v19
	v_cvt_pk_bf16_f32 v2, v2, s0
	ds_write_b16 v130, v2 offset:39648
	v_sub_f32_e32 v2, v78, v108
	v_mul_f32_e32 v2, v109, v2
	v_fmac_f32_e32 v59, v2, v55
	v_cvt_pk_bf16_f32 v2, v59, s0
	ds_write_b16 v130, v2 offset:39920
	v_cndmask_b32_e64 v2, v24, 0, s[24:25]
	v_cndmask_b32_e64 v54, v20, 0, s[26:27]
	v_cndmask_b32_e64 v52, v25, 0, s[28:29]
	v_cndmask_b32_e64 v55, v21, 0, s[30:31]
	v_cndmask_b32_e64 v53, v26, 0, s[34:35]
	v_cndmask_b32_e64 v56, v22, 0, s[36:37]
	v_cndmask_b32_e64 v57, v27, 0, s[38:39]
	v_cndmask_b32_e64 v58, v23, 0, s[40:41]
	v_cvt_pk_bf16_f32 v52, v2, v52
	v_cvt_pk_bf16_f32 v53, v53, v57
	v_cvt_pk_bf16_f32 v54, v54, v55
	v_cvt_pk_bf16_f32 v55, v56, v58
	ds_write_b128 v95, v[52:55] offset:1040
	v_lshlrev_b32_e32 v52, 16, v8
	v_sub_f32_e32 v52, v52, v108
	v_mul_f32_e32 v116, v109, v52
	s_nop 0
	s_nop 0
	v_and_b32_e32 v115, 0xffff0000, v8
	v_lshlrev_b32_e32 v114, 16, v9
	v_and_b32_e32 v113, 0xffff0000, v9
	v_lshlrev_b32_e32 v112, 16, v10
	v_and_b32_e32 v111, 0xffff0000, v10
	v_lshlrev_b32_e32 v110, 16, v11
	v_and_b32_e32 v2, 0xffff0000, v11
	v_sub_f32_e32 v2, v2, v108
	v_mul_f32_e32 v2, v109, v2
	s_mov_b32 s76, 4
	s_waitcnt vmcnt(0)
; __device__ __forceinline__ unsigned pk2(float lo, float hi) { f32x2 v = {lo, hi}; bf16x2_t b = __builtin_convertvector(v, bf16x2_t); return __builtin_bit_cast(unsigned, b); }
; #define LAS __attribute__((address_space(3)))
; __device__ __forceinline__ void unpack8(const u32x4 w, float (&f)[8]) { f[0] = bflo(w.x); f[1] = bfhi(w.x); f[2] = bflo(w.y); f[3] = bfhi(w.y); f[4] = bflo(w.z); f[5] = bfhi(w.z); f[6] = bflo(w.w); f[7] = bfhi(w.w); }
; __device__ __forceinline__ u32x4 pack8(const float (&f)[8]) { return (u32x4){pk2(f[0], f[1]), pk2(f[2], f[3]), pk2(f[4], f[5]), pk2(f[6], f[7])}; }
; #define GM_LOAD(G) do { const float* wsrc_ = a.wsp + ((size_t)(i * 4 + (G)) * 128 + stok) * 128 + 32 * spart; _Pragma("unroll") for (int q = 0; q < 4; ++q) { \
;         raw[q] = *(const u32x4*)(Z + (m0 + stok) * ZC + 2304 + (G) * 128 + 32 * spart + 8 * q); wr0[q] = *(const f32x4*)(wsrc_ + 8 * q); wr1[q] = *(const f32x4*)(wsrc_ + 8 * q + 4); } } while (0)
; __device__ __forceinline__ void post_phase(const KAS Args& a, LAS unsigned char* lds, int i, const int tid_, const int bid, const int nblk) {
;     ...
;               for (int q = 0; q < 4; ++q) { float sv[8], wv[8]; const int d0 = 32 * spart + 8 * q;
;                   unpack8(raw[q], sv);
; #pragma unroll
;                   for (int e = 0; e < 8; ++e) { const int dd = g * 128 + d0 + e; const float sn = (sv[e] - mean) * rstd * a.lng[i * 512 + dd] + a.lnb[i * 512 + dd];
;                       St[(d0 + e) * 136 + stok] = (bf16_t)(pk2(sn, 0.f) & 0xffffu); }
; #pragma unroll
;                   for (int e = 0; e < 4; ++e) { wv[e] = (d0 + e <= stok) ? wr0[q][e] : 0.f; wv[4 + e] = (d0 + 4 + e <= stok) ? wr1[q][e] : 0.f; }
;                   *(LAS u32x4*)(Wl + stok * 136 + d0) = pack8(wv); } }
;             if (g < 3) GM_LOAD(g + 1);
;             u32x2 uz[8];
; #pragma unroll
;             for (int dt = 0; dt < 8; ++dt) uz[dt] = *(const u32x2*)(Z + (m0 + etok) * ZC + 1792 + g * 128 + 16 * dt + 4 * l4);
;             const float bs = a.bsp[(i * 4 + g) * 128 + etok];
	v_fmac_f32_e32 v177, v2, v161
	v_fma_f32 v162, v116, v162, v188
	v_cvt_pk_bf16_f32 v162, v162, s0
	ds_write_b16 v130, v162 offset:40192
	v_sub_f32_e32 v162, v115, v108
	v_mul_f32_e32 v162, v109, v162
	v_fma_f32 v162, v162, v163, v189
	v_cvt_pk_bf16_f32 v162, v162, s0
	ds_write_b16 v130, v162 offset:40464
	v_sub_f32_e32 v162, v114, v108
	v_mul_f32_e32 v162, v109, v162
	v_fma_f32 v162, v162, v164, v190
	v_cvt_pk_bf16_f32 v162, v162, s0
	ds_write_b16 v130, v162 offset:40736
	v_sub_f32_e32 v162, v113, v108
	v_mul_f32_e32 v162, v109, v162
	v_fmac_f32_e32 v191, v162, v165
	v_cvt_pk_bf16_f32 v162, v191, s0
	ds_write_b16 v130, v162 offset:41008
	v_sub_f32_e32 v162, v112, v108
	v_mul_f32_e32 v162, v109, v162
	v_fma_f32 v158, v162, v158, v174
	v_cvt_pk_bf16_f32 v158, v158, s0
	ds_write_b16 v130, v158 offset:41280
	v_sub_f32_e32 v158, v111, v108
	v_mul_f32_e32 v158, v109, v158
	v_fma_f32 v158, v158, v159, v175
	v_cvt_pk_bf16_f32 v158, v158, s0
	ds_write_b16 v130, v158 offset:41552
	v_sub_f32_e32 v158, v110, v108
	v_mul_f32_e32 v158, v109, v158
	v_fma_f32 v158, v158, v160, v176
	v_cvt_pk_bf16_f32 v158, v158, s0
	v_cvt_pk_bf16_f32 v2, v177, s0
	ds_write_b16 v130, v158 offset:41824
	ds_write_b16 v130, v2 offset:42096
	v_cndmask_b32_e64 v2, v48, 0, s[42:43]
	v_cndmask_b32_e64 v158, v49, 0, s[46:47]
	v_cvt_pk_bf16_f32 v158, v2, v158
	v_lshlrev_b32_e32 v2, 16, v4
	v_sub_f32_e32 v2, v2, v108
	v_cndmask_b32_e64 v160, v44, 0, s[44:45]
	v_cndmask_b32_e64 v161, v45, 0, s[48:49]
	v_cndmask_b32_e64 v159, v50, 0, s[50:51]
	v_cndmask_b32_e64 v174, v46, 0, s[52:53]
	v_cndmask_b32_e64 v175, v51, 0, s[54:55]
	v_cndmask_b32_e64 v176, v47, 0, s[56:57]
	v_mul_f32_e32 v2, v109, v2
	v_cvt_pk_bf16_f32 v159, v159, v175
	v_cvt_pk_bf16_f32 v160, v160, v161
	v_cvt_pk_bf16_f32 v161, v174, v176
	v_fma_f32 v2, v2, v154, v170
	ds_write_b128 v95, v[158:161] offset:1056
	v_and_b32_e32 v158, 0xffff0000, v4
	v_cvt_pk_bf16_f32 v2, v2, s0
	ds_write_b16 v130, v2 offset:42368
	v_sub_f32_e32 v2, v158, v108
	v_mul_f32_e32 v2, v109, v2
	v_fma_f32 v2, v2, v155, v171
	v_lshlrev_b32_e32 v159, 16, v5
	v_cvt_pk_bf16_f32 v2, v2, s0
	ds_write_b16 v130, v2 offset:42640
	v_sub_f32_e32 v2, v159, v108
	v_mul_f32_e32 v2, v109, v2
	v_fma_f32 v2, v2, v156, v172
	v_and_b32_e32 v160, 0xffff0000, v5
	v_cvt_pk_bf16_f32 v2, v2, s0
	ds_write_b16 v130, v2 offset:42912
	v_sub_f32_e32 v2, v160, v108
	v_mul_f32_e32 v2, v109, v2
	v_fmac_f32_e32 v173, v2, v157
	v_lshlrev_b32_e32 v161, 16, v6
	v_cvt_pk_bf16_f32 v2, v173, s0
	ds_write_b16 v130, v2 offset:43184
	v_sub_f32_e32 v2, v161, v108
	v_mul_f32_e32 v2, v109, v2
	v_fma_f32 v2, v2, v150, v166
	v_and_b32_e32 v174, 0xffff0000, v6
	v_cvt_pk_bf16_f32 v2, v2, s0
	ds_write_b16 v130, v2 offset:43456
	v_sub_f32_e32 v2, v174, v108
	v_mul_f32_e32 v2, v109, v2
	v_fma_f32 v2, v2, v151, v167
	v_lshlrev_b32_e32 v175, 16, v7
	v_cvt_pk_bf16_f32 v2, v2, s0
	ds_write_b16 v130, v2 offset:43728
	v_sub_f32_e32 v2, v175, v108
	v_mul_f32_e32 v2, v109, v2
	v_fma_f32 v2, v2, v152, v168
	v_and_b32_e32 v176, 0xffff0000, v7
	v_cvt_pk_bf16_f32 v2, v2, s0
	ds_write_b16 v130, v2 offset:44000
	v_sub_f32_e32 v2, v176, v108
	v_mul_f32_e32 v2, v109, v2
	v_fmac_f32_e32 v169, v2, v153
	v_cvt_pk_bf16_f32 v2, v169, s0
	ds_write_b16 v130, v2 offset:44272
	v_cndmask_b32_e64 v2, v40, 0, s[58:59]
	v_cndmask_b32_e64 v152, v36, 0, s[60:61]
	v_cndmask_b32_e64 v150, v41, 0, s[62:63]
	v_cndmask_b32_e64 v153, v37, 0, s[64:65]
	v_cndmask_b32_e64 v151, v42, 0, s[66:67]
	v_cndmask_b32_e64 v154, v38, 0, s[68:69]
	v_cndmask_b32_e64 v155, v43, 0, s[70:71]
	v_cndmask_b32_e64 v156, v39, 0, s[72:73]
	v_cvt_pk_bf16_f32 v150, v2, v150
	v_cvt_pk_bf16_f32 v151, v151, v155
	v_cvt_pk_bf16_f32 v152, v152, v153
	v_cvt_pk_bf16_f32 v153, v154, v156
	ds_write_b128 v95, v[150:153] offset:1072
	s_lshl_b32 s92, s3, 1
	v_lshl_add_u64 v[56:57], v[104:105], 0, s[92:93]
	s_add_i32 vcc_lo, s2, s74
	global_load_dwordx2 v[122:123], v[56:57], off offset:3584
	global_load_dwordx2 v[120:121], v[56:57], off offset:3616
	global_load_dwordx2 v[118:119], v[56:57], off offset:3648
	global_load_dwordx2 v[116:117], v[56:57], off offset:3680
	global_load_dwordx2 v[114:115], v[56:57], off offset:3712
	global_load_dwordx2 v[112:113], v[56:57], off offset:3744
	global_load_dwordx2 v[110:111], v[56:57], off offset:3776
	global_load_dwordx2 v[108:109], v[56:57], off offset:3808
	v_lshl_add_u32 v58, vcc_lo, 7, v84
	v_ashrrev_i32_e32 v59, 31, v58
	v_lshl_add_u64 v[58:59], v[58:59], 2, s[86:87]
	global_load_dword v2, v[58:59], off
	s_cmp_eq_u32 s2, 3
	s_cbranch_scc1 .LBB0_164
	s_add_i32 s76, s2, 1
	s_add_i32 s92, s76, s74
	s_lshl_b64 vcc, s[92:93], 16
	s_lshl_b32 s92, s76, 8
	v_lshl_add_u64 v[48:49], v[92:93], 0, vcc
	v_lshl_add_u64 v[12:13], v[102:103], 0, s[92:93]
	global_load_dwordx4 v[4:7], v[12:13], off offset:48
	global_load_dwordx4 v[8:11], v[12:13], off offset:32
	global_load_dwordx4 v[16:19], v[12:13], off offset:16
	s_nop 0
	global_load_dwordx4 v[12:15], v[12:13], off
	s_nop 0
	global_load_dwordx4 v[20:23], v[48:49], off offset:48
	global_load_dwordx4 v[24:27], v[48:49], off offset:32
	global_load_dwordx4 v[28:31], v[48:49], off offset:16
	global_load_dwordx4 v[32:35], v[48:49], off
	global_load_dwordx4 v[36:39], v[48:49], off offset:112
	global_load_dwordx4 v[40:43], v[48:49], off offset:96
	global_load_dwordx4 v[44:47], v[48:49], off offset:80
	s_nop 0
	global_load_dwordx4 v[48:51], v[48:49], off offset:64
	s_branch .LBB0_164

; __device__ __forceinline__ void scan_load(const bf16_t* Z, const bf16_t* LO, size_t mrow0, int t0, int tid, int colb, u32x2 (&pz)[8]) {
;     const int t = t0 + (tid >> 4); const size_t m = mrow0 + t; const bf16_t* zr = Z + m * ZC + colb; const bf16_t* lo = LO + m * LOC + colb;
;     pz[0] = *(const u32x2*)(zr); pz[1] = *(const u32x2*)(zr + 512); pz[2] = *(const u32x2*)(zr + 1024);
;     if (t > 0) { pz[3] = *(const u32x2*)(zr - ZC); pz[4] = *(const u32x2*)(zr + 512 - ZC); pz[5] = *(const u32x2*)(zr + 1024 - ZC); } else { pz[3] = (u32x2){0u, 0u}; pz[4] = (u32x2){0u, 0u}; pz[5] = (u32x2){0u, 0u}; }
;     pz[6] = *(const u32x2*)(lo); pz[7] = *(const u32x2*)(lo + 512);
; }
; __device__ __forceinline__ void scan_phase(const KAS Args& a, LAS unsigned char* lds, int i, const int tid_, const int bid, const int nblk) {
;     ...
;     for (int unit = bid; unit < 256; unit += nblk) {
;         const int bh = unit >> 1, half = unit & 1, b = bh >> 3, h = bh & 7, colb = h * 64 + 4 * (tid & 15);
;         float mu_r[4], mu_k[4], mu_v[4], kkc[4], kac[4], rkc[4];
; #pragma unroll
;         for (int e = 0; e < 4; ++e) { mu_r[e] = a.mu[i * 1792 + colb + e]; mu_k[e] = a.mu[i * 1792 + 512 + colb + e]; mu_v[e] = a.mu[i * 1792 + 1024 + colb + e];
;             kkc[e] = a.kk[i * 512 + colb + e]; kac[e] = a.ka[i * 512 + colb + e]; rkc[e] = a.rk[i * 512 + colb + e]; }
;         const size_t mrow0 = (size_t)b * T;
;         const int rl = wave * 4 + (lane >> 4), cgp = lane & 15;
;         f32x4 S = {0.f, 0.f, 0.f, 0.f};
;         u32x2 pz[8];
;         __syncthreads();
;         scan_load(Z, LO, mrow0, 0, tid, colb, pz);
;         scan_stage(pz, bufs, RKB, mrow0, 0, tid, h, half, mu_r, mu_k, mu_v, kkc, kac, rkc);
;         __syncthreads();
;         for (int c = 0; c < T / TC; ++c) {
;             const bool more = (c + 1 < T / TC);
;             if (more) scan_load(Z, LO, mrow0, (c + 1) * TC, tid, colb, pz);
.LBB0_181:
	s_or_b64 exec, exec, s[2:3]
	s_lshr_b32 s2, s66, 1
	s_and_b32 s2, s2, 7
	s_lshl_b32 s62, s2, 7
	v_cndmask_b32_e64 v2, 0, 1, s[56:57]
	s_lshl_b32 s63, s2, 2
	s_lshl_b64 s[2:3], s[60:61], 22
	v_lshlrev_b32_e32 v28, 6, v2
	s_or_b32 s2, s2, s62
	v_or_b32_e32 v28, s2, v28
	v_mov_b32_e32 v29, s3
	s_lshl_b64 s[2:3], s[60:61], 17
	v_lshl_add_u64 v[96:97], v[70:71], 0, v[28:29]
	v_lshl_add_u64 v[98:99], v[72:73], 0, v[28:29]
	s_or_b32 s2, s2, s63
	v_mov_b32_e32 v28, 0xc00000
	v_lshl_or_b32 v2, v111, 1, s62
	v_lshl_add_u64 v[100:101], s[2:3], 0, v[74:75]
	v_mad_i64_i32 v[28:29], s[2:3], s60, v28, v[76:77]
	v_lshl_add_u64 v[102:103], v[28:29], 0, v[2:3]
	v_mov_b32_e32 v28, 0x1600000
	v_mad_i64_i32 v[28:29], s[2:3], s60, v28, v[78:79]
	v_mov_b32_e32 v36, 0
	v_lshl_add_u64 v[104:105], v[28:29], 0, v[2:3]
	s_mov_b32 s67, 0
	v_mov_b32_e32 v121, v119
	v_mov_b32_e32 v37, v36
	v_mov_b32_e32 v38, v36
	v_mov_b32_e32 v39, v36
	v_lshl_add_u64 v[28:29], s[88:89], 0, v[104:105]
	v_add_co_u32_e32 v30, vcc, 0x1382c000, v28
	s_nop 1
	v_addc_co_u32_e32 v31, vcc, 0, v29, vcc
	global_load_dwordx2 v[80:81], v[30:31], off
	global_load_dwordx2 v[82:83], v[30:31], off offset:1024
	global_load_dwordx2 v[84:85], v[30:31], off offset:2048
	v_cmp_gt_i32_e32 vcc, 1, v121
	s_and_saveexec_b64 s[2:3], vcc
	s_xor_b64 s[2:3], exec, s[2:3]
	s_or_saveexec_b64 s[16:17], s[2:3]
	s_waitcnt vmcnt(9)
	v_mov_b32_e32 v86, 0
	v_mov_b32_e32 v87, 0
	s_waitcnt vmcnt(8)
	v_mov_b32_e32 v88, 0
	v_mov_b32_e32 v89, 0
	s_waitcnt vmcnt(7)
	v_mov_b32_e32 v90, 0
	v_mov_b32_e32 v91, 0
	s_xor_b64 exec, exec, s[16:17]
	s_cbranch_execz .Lscs_189
	v_add_co_u32_e32 v30, vcc, 0x1382a000, v28
	s_nop 1
	v_addc_co_u32_e32 v31, vcc, 0, v29, vcc
	v_add_co_u32_e32 v28, vcc, 0x1382b000, v28
	s_nop 1
	v_addc_co_u32_e32 v29, vcc, 0, v29, vcc
	global_load_dwordx2 v[86:87], v[30:31], off offset:2560
	global_load_dwordx2 v[88:89], v[30:31], off offset:3584
	global_load_dwordx2 v[90:91], v[28:29], off offset:512
.Lscs_189:
	s_or_b64 exec, exec, s[16:17]
	v_lshl_add_u64 v[28:29], s[88:89], 0, v[102:103]
	v_add_co_u32_e32 v28, vcc, 0x31818000, v28
	s_nop 1
	v_addc_co_u32_e32 v29, vcc, 0, v29, vcc
	global_load_dwordx2 v[92:93], v[28:29], off
	global_load_dwordx2 v[94:95], v[28:29], off offset:1024
	s_mov_b64 s[2:3], 0x18000
	v_lshl_add_u64 v[102:103], v[102:103], 0, s[2:3]
	s_mov_b64 s[2:3], 0x2c000
	v_lshl_add_u64 v[104:105], v[104:105], 0, s[2:3]
	v_add_u32_e32 v121, 32, v121
	s_waitcnt lgkmcnt(0)
	s_barrier
	s_branch .LBB0_184
.LBB0_182:
	s_or_b64 exec, exec, s[2:3]
	s_cmpk_ge_i32 s67, 0x7e
	s_cbranch_scc1 .LBB0_183
	v_lshl_add_u64 v[28:29], s[88:89], 0, v[104:105]
	v_add_co_u32_e32 v30, vcc, 0x1382c000, v28
	s_nop 1
	v_addc_co_u32_e32 v31, vcc, 0, v29, vcc
	global_load_dwordx2 v[80:81], v[30:31], off
	global_load_dwordx2 v[82:83], v[30:31], off offset:1024
	global_load_dwordx2 v[84:85], v[30:31], off offset:2048
	v_cmp_gt_i32_e32 vcc, 1, v121
	s_and_saveexec_b64 s[2:3], vcc
	s_xor_b64 s[2:3], exec, s[2:3]
	s_or_saveexec_b64 s[16:17], s[2:3]
	s_waitcnt vmcnt(9)
	v_mov_b32_e32 v86, 0
	v_mov_b32_e32 v87, 0
	s_waitcnt vmcnt(8)
	v_mov_b32_e32 v88, 0
	v_mov_b32_e32 v89, 0
	s_waitcnt vmcnt(7)
	v_mov_b32_e32 v90, 0
	v_mov_b32_e32 v91, 0
	s_xor_b64 exec, exec, s[16:17]
	s_cbranch_execz .Lscl_189
	v_add_co_u32_e32 v30, vcc, 0x1382a000, v28
	s_nop 1
	v_addc_co_u32_e32 v31, vcc, 0, v29, vcc
	v_add_co_u32_e32 v28, vcc, 0x1382b000, v28
	s_nop 1
	v_addc_co_u32_e32 v29, vcc, 0, v29, vcc
	global_load_dwordx2 v[86:87], v[30:31], off offset:2560
	global_load_dwordx2 v[88:89], v[30:31], off offset:3584
	global_load_dwordx2 v[90:91], v[28:29], off offset:512
.Lscl_189:
	s_or_b64 exec, exec, s[16:17]
	v_lshl_add_u64 v[28:29], s[88:89], 0, v[102:103]
	v_add_co_u32_e32 v28, vcc, 0x31818000, v28
	s_nop 1
	v_addc_co_u32_e32 v29, vcc, 0, v29, vcc
	global_load_dwordx2 v[92:93], v[28:29], off
	global_load_dwordx2 v[94:95], v[28:29], off offset:1024

; #define LAS __attribute__((address_space(3)))
; __device__ __forceinline__ float row16_sum(float x) { x += dpp_mov<0xB1>(x); x += dpp_mov<0x4E>(x); x += dpp_mov<0x124>(x); x += dpp_mov<0x128>(x); return x; }
; __device__ __forceinline__ void scan_phase(const KAS Args& a, LAS unsigned char* lds, int i, const int tid_, const int bid, const int nblk) {
;     ...
;         for (int c = 0; c < T / TC; ++c) {
;             const bool more = (c + 1 < T / TC);
;             if (more) scan_load(Z, LO, mrow0, (c + 1) * TC, tid, colb, pz);
;             const LAS float* buf = bufs + (c & 1) * (TC * SST); LAS float* yb = ybuf + (c & 1) * (TC * 32);
;             {
;                 const LAS float* sb = buf + 4 * cgp; const LAS float* vb = buf + 320 + rl;
;                 f32x4 kk4 = *(const LAS f32x4*)(sb), nb4 = *(const LAS f32x4*)(sb + 64), w4 = *(const LAS f32x4*)(sb + 128), k4 = *(const LAS f32x4*)(sb + 192), r4 = *(const LAS f32x4*)(sb + 256);
;                 float v = vb[0], ysel = 0.f;
; #pragma unroll
;                 for (int t = 0; t < TC; ++t) {
;                     f32x4 kk4n = kk4, nb4n = nb4, w4n = w4, k4n = k4, r4n = r4; float vn = v;
;                     if (t + 1 < TC) { const LAS float* sn = sb + (t + 1) * SST;
;                         kk4n = *(const LAS f32x4*)(sn); nb4n = *(const LAS f32x4*)(sn + 64); w4n = *(const LAS f32x4*)(sn + 128); k4n = *(const LAS f32x4*)(sn + 192); r4n = *(const LAS f32x4*)(sn + 256); vn = vb[(t + 1) * SST]; }
;                     __builtin_amdgcn_sched_barrier(0x6);
;                     float sa = fmaf(S[3], kk4[3], fmaf(S[2], kk4[2], fmaf(S[1], kk4[1], S[0] * kk4[0])));
;                     const f32x4 Tm = S * w4 + k4 * v;
;                     sa = row16_sum(sa);
;                     S = Tm + nb4 * sa;
;                     float y = fmaf(S[3], r4[3], fmaf(S[2], r4[2], fmaf(S[1], r4[1], S[0] * r4[0]))); y = row16_sum(y);
;                     ysel = (cgp == (t & 15)) ? y : ysel;
;                     if ((t & 15) == 15) yb[(t - 15 + cgp) * 32 + rl] = ysel;
;                     kk4 = kk4n; nb4 = nb4n; w4 = w4n; k4 = k4n; r4 = r4n; v = vn; }
.LBB0_184:
	s_cmpk_lg_i32 s67, 0x7f
	s_cselect_b64 s[60:61], -1, 0
.LBB0_190:
	s_and_b32 s2, s67, 1
	s_mul_i32 s3, s2, 0xb000
	s_add_i32 s3, s94, s3
	v_add_u32_e32 v124, s3, v114
	v_add_u32_e32 v110, s3, v120
	ds_read_b128 v[136:139], v124 offset:0
	ds_read_b128 v[140:143], v124 offset:256
	ds_read_b128 v[144:147], v124 offset:512
	ds_read_b128 v[148:151], v124 offset:768
	ds_read_b128 v[152:155], v124 offset:1024
	ds_read_b32 v156, v110 offset:1280
	ds_read_b128 v[160:163], v124 offset:1408
	ds_read_b128 v[164:167], v124 offset:1664
	ds_read_b128 v[168:171], v124 offset:1920
	ds_read_b128 v[172:175], v124 offset:2176
	ds_read_b128 v[176:179], v124 offset:2432
	ds_read_b32 v158, v110 offset:2688
	ds_read_b128 v[188:191], v124 offset:2816
	ds_read_b128 v[192:195], v124 offset:3072
	ds_read_b128 v[196:199], v124 offset:3328
	ds_read_b128 v[200:203], v124 offset:3584
	ds_read_b128 v[204:207], v124 offset:3840
	ds_read_b32 v208, v110 offset:4096
	s_lshl_b32 s2, s2, 12
	s_add_i32 s63, s64, s2
	s_add_i32 s62, s67, 1
	s_andn2_b64 vcc, exec, s[60:61]
	s_mov_b32 s8, 0xaaaaaaaa
	s_mov_b32 s9, 0xaaaaaaaa
	s_mov_b32 s10, 0xcccccccc
	s_mov_b32 s11, 0xcccccccc
	s_mov_b32 s12, 0xf0f0f0f0
	s_mov_b32 s13, 0xf0f0f0f0
	s_mov_b32 s14, 0xff00ff00
	s_mov_b32 s15, 0xff00ff00
	v_add3_u32 v122, s63, v120, v118
	s_waitcnt lgkmcnt(15)
	v_mul_f32_e32 v44, v36, v136
	v_fmac_f32_e32 v44, v37, v137
	v_fmac_f32_e32 v44, v38, v138
	v_fmac_f32_e32 v44, v39, v139
	s_waitcnt lgkmcnt(12)
	v_pk_mul_f32 v[40:41], v[148:149], v[156:157] op_sel_hi:[1,0]
	v_pk_mul_f32 v[42:43], v[150:151], v[156:157] op_sel_hi:[1,0]
	v_add_f32_dpp v2, v44, v44 quad_perm:[1,0,3,2] row_mask:0xf bank_mask:0xf bound_ctrl:1
	v_pk_fma_f32 v[40:41], v[36:37], v[144:145], v[40:41]
	v_pk_fma_f32 v[42:43], v[38:39], v[146:147], v[42:43]
	v_add_f32_dpp v2, v2, v2 quad_perm:[2,3,0,1] row_mask:0xf bank_mask:0xf bound_ctrl:1
	s_nop 1
	v_add_f32_dpp v2, v2, v2 row_ror:4 row_mask:0xf bank_mask:0xf bound_ctrl:1
	s_nop 1
	v_add_f32_dpp v2, v2, v2 row_ror:8 row_mask:0xf bank_mask:0xf bound_ctrl:1
	v_pk_fma_f32 v[36:37], v[140:141], v[2:3], v[40:41] op_sel_hi:[1,0,1]
	v_pk_fma_f32 v[38:39], v[142:143], v[2:3], v[42:43] op_sel_hi:[1,0,1]
	s_waitcnt lgkmcnt(11)
	v_mul_f32_e32 v44, v36, v160
	v_mul_f32_e32 v45, v152, v36
	v_fmac_f32_e32 v44, v37, v161
	v_fmac_f32_e32 v45, v37, v153
	v_fmac_f32_e32 v44, v38, v162
	v_fmac_f32_e32 v45, v38, v154
	v_fmac_f32_e32 v44, v39, v163
	v_fmac_f32_e32 v45, v39, v155
	s_waitcnt lgkmcnt(6)
	v_pk_mul_f32 v[40:41], v[172:173], v[158:159] op_sel_hi:[1,0]
	v_pk_mul_f32 v[42:43], v[174:175], v[158:159] op_sel_hi:[1,0]
	v_add_f32_dpp v2, v44, v44 quad_perm:[1,0,3,2] row_mask:0xf bank_mask:0xf bound_ctrl:1
	v_pk_fma_f32 v[40:41], v[36:37], v[168:169], v[40:41]
	v_pk_fma_f32 v[42:43], v[38:39], v[170:171], v[42:43]
	v_add_f32_dpp v2, v2, v2 quad_perm:[2,3,0,1] row_mask:0xf bank_mask:0xf bound_ctrl:1
	ds_read_b128 v[136:139], v124 offset:4224
	ds_read_b128 v[140:143], v124 offset:4480
	ds_read_b128 v[144:147], v124 offset:4736
	ds_read_b128 v[148:151], v124 offset:4992
	ds_read_b128 v[152:155], v124 offset:5248
	ds_read_b32 v156, v110 offset:5504
	s_nop 1
	v_add_f32_dpp v2, v2, v2 row_ror:4 row_mask:0xf bank_mask:0xf bound_ctrl:1
	s_nop 1
	v_add_f32_dpp v2, v2, v2 row_ror:8 row_mask:0xf bank_mask:0xf bound_ctrl:1
	v_pk_fma_f32 v[36:37], v[164:165], v[2:3], v[40:41] op_sel_hi:[1,0,1]
	v_pk_fma_f32 v[38:39], v[166:167], v[2:3], v[42:43] op_sel_hi:[1,0,1]
	s_waitcnt lgkmcnt(11)
	v_mul_f32_e32 v44, v36, v188
	v_mul_f32_e32 v46, v176, v36
	v_fmac_f32_e32 v44, v37, v189
	v_fmac_f32_e32 v46, v37, v177
	v_fmac_f32_e32 v44, v38, v190
	v_fmac_f32_e32 v46, v38, v178
	v_fmac_f32_e32 v44, v39, v191
	v_fmac_f32_e32 v46, v39, v179
	s_waitcnt lgkmcnt(6)
	v_pk_mul_f32 v[40:41], v[200:201], v[208:209] op_sel_hi:[1,0]
	v_pk_mul_f32 v[42:43], v[202:203], v[208:209] op_sel_hi:[1,0]
	v_add_f32_dpp v2, v44, v44 quad_perm:[1,0,3,2] row_mask:0xf bank_mask:0xf bound_ctrl:1
	v_pk_fma_f32 v[40:41], v[36:37], v[196:197], v[40:41]
	v_pk_fma_f32 v[42:43], v[38:39], v[198:199], v[42:43]
	v_add_f32_dpp v2, v2, v2 quad_perm:[2,3,0,1] row_mask:0xf bank_mask:0xf bound_ctrl:1
	v_cndmask_b32_e64 v56, v45, v46, s[8:9]
	v_cndmask_b32_e64 v57, v46, v45, s[8:9]
	s_nop 1
	v_add_f32_dpp v47, v57, v56 quad_perm:[1,0,3,2] row_mask:0xf bank_mask:0xf bound_ctrl:1
	ds_read_b128 v[160:163], v124 offset:5632
	ds_read_b128 v[164:167], v124 offset:5888
	ds_read_b128 v[168:171], v124 offset:6144
	ds_read_b128 v[172:175], v124 offset:6400
	ds_read_b128 v[176:179], v124 offset:6656
	ds_read_b32 v158, v110 offset:6912
	v_add_f32_dpp v2, v2, v2 row_ror:4 row_mask:0xf bank_mask:0xf bound_ctrl:1
	s_nop 1
	v_add_f32_dpp v2, v2, v2 row_ror:8 row_mask:0xf bank_mask:0xf bound_ctrl:1
	v_pk_fma_f32 v[36:37], v[192:193], v[2:3], v[40:41] op_sel_hi:[1,0,1]
	v_pk_fma_f32 v[38:39], v[194:195], v[2:3], v[42:43] op_sel_hi:[1,0,1]
	s_waitcnt lgkmcnt(11)
	v_mul_f32_e32 v44, v36, v136
	v_mul_f32_e32 v48, v204, v36
	v_fmac_f32_e32 v44, v37, v137
	v_fmac_f32_e32 v48, v37, v205
	v_fmac_f32_e32 v44, v38, v138
	v_fmac_f32_e32 v48, v38, v206
	v_fmac_f32_e32 v44, v39, v139
	v_fmac_f32_e32 v48, v39, v207
	s_waitcnt lgkmcnt(6)
; #define LAS __attribute__((address_space(3)))
; __device__ __forceinline__ float row16_sum(float x) { x += dpp_mov<0xB1>(x); x += dpp_mov<0x4E>(x); x += dpp_mov<0x124>(x); x += dpp_mov<0x128>(x); return x; }
; __device__ __forceinline__ void scan_phase(const KAS Args& a, LAS unsigned char* lds, int i, const int tid_, const int bid, const int nblk) {
;     ...
;                 for (int t = 0; t < TC; ++t) {
;                     f32x4 kk4n = kk4, nb4n = nb4, w4n = w4, k4n = k4, r4n = r4; float vn = v;
;                     if (t + 1 < TC) { const LAS float* sn = sb + (t + 1) * SST;
;                         kk4n = *(const LAS f32x4*)(sn); nb4n = *(const LAS f32x4*)(sn + 64); w4n = *(const LAS f32x4*)(sn + 128); k4n = *(const LAS f32x4*)(sn + 192); r4n = *(const LAS f32x4*)(sn + 256); vn = vb[(t + 1) * SST]; }
;                     __builtin_amdgcn_sched_barrier(0x6);
;                     float sa = fmaf(S[3], kk4[3], fmaf(S[2], kk4[2], fmaf(S[1], kk4[1], S[0] * kk4[0])));
;                     const f32x4 Tm = S * w4 + k4 * v;
;                     sa = row16_sum(sa);
;                     S = Tm + nb4 * sa;
;                     float y = fmaf(S[3], r4[3], fmaf(S[2], r4[2], fmaf(S[1], r4[1], S[0] * r4[0]))); y = row16_sum(y);
;                     ysel = (cgp == (t & 15)) ? y : ysel;
;                     if ((t & 15) == 15) yb[(t - 15 + cgp) * 32 + rl] = ysel;
;                     kk4 = kk4n; nb4 = nb4n; w4 = w4n; k4 = k4n; r4 = r4n; v = vn; }
	v_pk_mul_f32 v[40:41], v[148:149], v[156:157] op_sel_hi:[1,0]
	v_pk_mul_f32 v[42:43], v[150:151], v[156:157] op_sel_hi:[1,0]
	v_add_f32_dpp v2, v44, v44 quad_perm:[1,0,3,2] row_mask:0xf bank_mask:0xf bound_ctrl:1
	v_pk_fma_f32 v[40:41], v[36:37], v[144:145], v[40:41]
	v_pk_fma_f32 v[42:43], v[38:39], v[146:147], v[42:43]
	v_add_f32_dpp v2, v2, v2 quad_perm:[2,3,0,1] row_mask:0xf bank_mask:0xf bound_ctrl:1
	ds_read_b128 v[188:191], v124 offset:7040
	ds_read_b128 v[192:195], v124 offset:7296
	ds_read_b128 v[196:199], v124 offset:7552
	ds_read_b128 v[200:203], v124 offset:7808
	ds_read_b128 v[204:207], v124 offset:8064
	ds_read_b32 v208, v110 offset:8320
	s_nop 1
	v_add_f32_dpp v2, v2, v2 row_ror:4 row_mask:0xf bank_mask:0xf bound_ctrl:1
	s_nop 1
	v_add_f32_dpp v2, v2, v2 row_ror:8 row_mask:0xf bank_mask:0xf bound_ctrl:1
	v_pk_fma_f32 v[36:37], v[140:141], v[2:3], v[40:41] op_sel_hi:[1,0,1]
	v_pk_fma_f32 v[38:39], v[142:143], v[2:3], v[42:43] op_sel_hi:[1,0,1]
	s_waitcnt lgkmcnt(11)
	v_mul_f32_e32 v44, v36, v160
	v_mul_f32_e32 v49, v152, v36
	v_fmac_f32_e32 v44, v37, v161
	v_fmac_f32_e32 v49, v37, v153
	v_fmac_f32_e32 v44, v38, v162
	v_fmac_f32_e32 v49, v38, v154
	v_fmac_f32_e32 v44, v39, v163
	v_fmac_f32_e32 v49, v39, v155
	s_waitcnt lgkmcnt(6)
	v_pk_mul_f32 v[40:41], v[172:173], v[158:159] op_sel_hi:[1,0]
	v_pk_mul_f32 v[42:43], v[174:175], v[158:159] op_sel_hi:[1,0]
	v_add_f32_dpp v2, v44, v44 quad_perm:[1,0,3,2] row_mask:0xf bank_mask:0xf bound_ctrl:1
	v_pk_fma_f32 v[40:41], v[36:37], v[168:169], v[40:41]
	v_pk_fma_f32 v[42:43], v[38:39], v[170:171], v[42:43]
	v_add_f32_dpp v2, v2, v2 quad_perm:[2,3,0,1] row_mask:0xf bank_mask:0xf bound_ctrl:1
	v_cndmask_b32_e64 v56, v48, v49, s[8:9]
	v_cndmask_b32_e64 v57, v49, v48, s[8:9]
	s_nop 1
	v_add_f32_dpp v50, v57, v56 quad_perm:[1,0,3,2] row_mask:0xf bank_mask:0xf bound_ctrl:1
	v_cndmask_b32_e64 v56, v47, v50, s[10:11]
	v_cndmask_b32_e64 v57, v50, v47, s[10:11]
	s_nop 1
	v_add_f32_dpp v51, v57, v56 quad_perm:[2,3,0,1] row_mask:0xf bank_mask:0xf bound_ctrl:1
	ds_read_b128 v[136:139], v124 offset:8448
	ds_read_b128 v[140:143], v124 offset:8704
	ds_read_b128 v[144:147], v124 offset:8960
	ds_read_b128 v[148:151], v124 offset:9216
	ds_read_b128 v[152:155], v124 offset:9472
	ds_read_b32 v156, v110 offset:9728
	v_add_f32_dpp v2, v2, v2 row_ror:4 row_mask:0xf bank_mask:0xf bound_ctrl:1
	s_nop 1
	v_add_f32_dpp v2, v2, v2 row_ror:8 row_mask:0xf bank_mask:0xf bound_ctrl:1
	v_pk_fma_f32 v[36:37], v[164:165], v[2:3], v[40:41] op_sel_hi:[1,0,1]
	v_pk_fma_f32 v[38:39], v[166:167], v[2:3], v[42:43] op_sel_hi:[1,0,1]
	s_waitcnt lgkmcnt(11)
	v_mul_f32_e32 v44, v36, v188
	v_mul_f32_e32 v52, v176, v36
	v_fmac_f32_e32 v44, v37, v189
	v_fmac_f32_e32 v52, v37, v177
	v_fmac_f32_e32 v44, v38, v190
	v_fmac_f32_e32 v52, v38, v178
	v_fmac_f32_e32 v44, v39, v191
	v_fmac_f32_e32 v52, v39, v179
	s_waitcnt lgkmcnt(6)
	v_pk_mul_f32 v[40:41], v[200:201], v[208:209] op_sel_hi:[1,0]
	v_pk_mul_f32 v[42:43], v[202:203], v[208:209] op_sel_hi:[1,0]
	v_add_f32_dpp v2, v44, v44 quad_perm:[1,0,3,2] row_mask:0xf bank_mask:0xf bound_ctrl:1
	v_pk_fma_f32 v[40:41], v[36:37], v[196:197], v[40:41]
	v_pk_fma_f32 v[42:43], v[38:39], v[198:199], v[42:43]
	v_add_f32_dpp v2, v2, v2 quad_perm:[2,3,0,1] row_mask:0xf bank_mask:0xf bound_ctrl:1
	ds_read_b128 v[160:163], v124 offset:9856
	ds_read_b128 v[164:167], v124 offset:10112
	ds_read_b128 v[168:171], v124 offset:10368
	ds_read_b128 v[172:175], v124 offset:10624
	ds_read_b128 v[176:179], v124 offset:10880
	ds_read_b32 v158, v110 offset:11136
	s_nop 1
	v_add_f32_dpp v2, v2, v2 row_ror:4 row_mask:0xf bank_mask:0xf bound_ctrl:1
	s_nop 1
	v_add_f32_dpp v2, v2, v2 row_ror:8 row_mask:0xf bank_mask:0xf bound_ctrl:1
	v_pk_fma_f32 v[36:37], v[192:193], v[2:3], v[40:41] op_sel_hi:[1,0,1]
	v_pk_fma_f32 v[38:39], v[194:195], v[2:3], v[42:43] op_sel_hi:[1,0,1]
	s_waitcnt lgkmcnt(11)
	v_mul_f32_e32 v44, v36, v136
	v_mul_f32_e32 v53, v204, v36
	v_fmac_f32_e32 v44, v37, v137
	v_fmac_f32_e32 v53, v37, v205
	v_fmac_f32_e32 v44, v38, v138
	v_fmac_f32_e32 v53, v38, v206
	v_fmac_f32_e32 v44, v39, v139
	v_fmac_f32_e32 v53, v39, v207
	s_waitcnt lgkmcnt(6)
	v_pk_mul_f32 v[40:41], v[148:149], v[156:157] op_sel_hi:[1,0]
	v_pk_mul_f32 v[42:43], v[150:151], v[156:157] op_sel_hi:[1,0]
	v_add_f32_dpp v2, v44, v44 quad_perm:[1,0,3,2] row_mask:0xf bank_mask:0xf bound_ctrl:1
	v_pk_fma_f32 v[40:41], v[36:37], v[144:145], v[40:41]
	v_pk_fma_f32 v[42:43], v[38:39], v[146:147], v[42:43]
	v_add_f32_dpp v2, v2, v2 quad_perm:[2,3,0,1] row_mask:0xf bank_mask:0xf bound_ctrl:1
	v_cndmask_b32_e64 v56, v52, v53, s[8:9]
	v_cndmask_b32_e64 v57, v53, v52, s[8:9]
	s_nop 1
	v_add_f32_dpp v54, v57, v56 quad_perm:[1,0,3,2] row_mask:0xf bank_mask:0xf bound_ctrl:1
	ds_read_b128 v[188:191], v124 offset:11264
	ds_read_b128 v[192:195], v124 offset:11520
	ds_read_b128 v[196:199], v124 offset:11776
	ds_read_b128 v[200:203], v124 offset:12032
	ds_read_b128 v[204:207], v124 offset:12288
	ds_read_b32 v208, v110 offset:12544
	v_add_f32_dpp v2, v2, v2 row_ror:4 row_mask:0xf bank_mask:0xf bound_ctrl:1
	s_nop 1
	v_add_f32_dpp v2, v2, v2 row_ror:8 row_mask:0xf bank_mask:0xf bound_ctrl:1
	v_pk_fma_f32 v[36:37], v[140:141], v[2:3], v[40:41] op_sel_hi:[1,0,1]
	v_pk_fma_f32 v[38:39], v[142:143], v[2:3], v[42:43] op_sel_hi:[1,0,1]
	s_waitcnt lgkmcnt(11)
	v_mul_f32_e32 v44, v36, v160
	v_mul_f32_e32 v55, v152, v36
	v_fmac_f32_e32 v44, v37, v161
	v_fmac_f32_e32 v55, v37, v153
	v_fmac_f32_e32 v44, v38, v162
	v_fmac_f32_e32 v55, v38, v154
	v_fmac_f32_e32 v44, v39, v163
	v_fmac_f32_e32 v55, v39, v155
	s_waitcnt lgkmcnt(6)
; #define LAS __attribute__((address_space(3)))
; __device__ __forceinline__ float row16_sum(float x) { x += dpp_mov<0xB1>(x); x += dpp_mov<0x4E>(x); x += dpp_mov<0x124>(x); x += dpp_mov<0x128>(x); return x; }
; __device__ __forceinline__ void scan_phase(const KAS Args& a, LAS unsigned char* lds, int i, const int tid_, const int bid, const int nblk) {
;     ...
;                 for (int t = 0; t < TC; ++t) {
;                     f32x4 kk4n = kk4, nb4n = nb4, w4n = w4, k4n = k4, r4n = r4; float vn = v;
;                     if (t + 1 < TC) { const LAS float* sn = sb + (t + 1) * SST;
;                         kk4n = *(const LAS f32x4*)(sn); nb4n = *(const LAS f32x4*)(sn + 64); w4n = *(const LAS f32x4*)(sn + 128); k4n = *(const LAS f32x4*)(sn + 192); r4n = *(const LAS f32x4*)(sn + 256); vn = vb[(t + 1) * SST]; }
;                     __builtin_amdgcn_sched_barrier(0x6);
;                     float sa = fmaf(S[3], kk4[3], fmaf(S[2], kk4[2], fmaf(S[1], kk4[1], S[0] * kk4[0])));
;                     const f32x4 Tm = S * w4 + k4 * v;
;                     sa = row16_sum(sa);
;                     S = Tm + nb4 * sa;
;                     float y = fmaf(S[3], r4[3], fmaf(S[2], r4[2], fmaf(S[1], r4[1], S[0] * r4[0]))); y = row16_sum(y);
;                     ysel = (cgp == (t & 15)) ? y : ysel;
;                     if ((t & 15) == 15) yb[(t - 15 + cgp) * 32 + rl] = ysel;
;                     kk4 = kk4n; nb4 = nb4n; w4 = w4n; k4 = k4n; r4 = r4n; v = vn; }
	v_pk_mul_f32 v[40:41], v[172:173], v[158:159] op_sel_hi:[1,0]
	v_pk_mul_f32 v[42:43], v[174:175], v[158:159] op_sel_hi:[1,0]
	v_add_f32_dpp v2, v44, v44 quad_perm:[1,0,3,2] row_mask:0xf bank_mask:0xf bound_ctrl:1
	v_pk_fma_f32 v[40:41], v[36:37], v[168:169], v[40:41]
	v_pk_fma_f32 v[42:43], v[38:39], v[170:171], v[42:43]
	v_add_f32_dpp v2, v2, v2 quad_perm:[2,3,0,1] row_mask:0xf bank_mask:0xf bound_ctrl:1
	ds_read_b128 v[136:139], v124 offset:12672
	ds_read_b128 v[140:143], v124 offset:12928
	ds_read_b128 v[144:147], v124 offset:13184
	ds_read_b128 v[148:151], v124 offset:13440
	ds_read_b128 v[152:155], v124 offset:13696
	ds_read_b32 v156, v110 offset:13952
	s_nop 1
	v_add_f32_dpp v2, v2, v2 row_ror:4 row_mask:0xf bank_mask:0xf bound_ctrl:1
	s_nop 1
	v_add_f32_dpp v2, v2, v2 row_ror:8 row_mask:0xf bank_mask:0xf bound_ctrl:1
	v_pk_fma_f32 v[36:37], v[164:165], v[2:3], v[40:41] op_sel_hi:[1,0,1]
	v_pk_fma_f32 v[38:39], v[166:167], v[2:3], v[42:43] op_sel_hi:[1,0,1]
	s_waitcnt lgkmcnt(11)
	v_mul_f32_e32 v44, v36, v188
	v_mul_f32_e32 v58, v176, v36
	v_fmac_f32_e32 v44, v37, v189
	v_fmac_f32_e32 v58, v37, v177
	v_fmac_f32_e32 v44, v38, v190
	v_fmac_f32_e32 v58, v38, v178
	v_fmac_f32_e32 v44, v39, v191
	v_fmac_f32_e32 v58, v39, v179
	s_waitcnt lgkmcnt(6)
	v_pk_mul_f32 v[40:41], v[200:201], v[208:209] op_sel_hi:[1,0]
	v_pk_mul_f32 v[42:43], v[202:203], v[208:209] op_sel_hi:[1,0]
	v_add_f32_dpp v2, v44, v44 quad_perm:[1,0,3,2] row_mask:0xf bank_mask:0xf bound_ctrl:1
	v_pk_fma_f32 v[40:41], v[36:37], v[196:197], v[40:41]
	v_pk_fma_f32 v[42:43], v[38:39], v[198:199], v[42:43]
	v_add_f32_dpp v2, v2, v2 quad_perm:[2,3,0,1] row_mask:0xf bank_mask:0xf bound_ctrl:1
	v_cndmask_b32_e64 v56, v55, v58, s[8:9]
	v_cndmask_b32_e64 v57, v58, v55, s[8:9]
	s_nop 1
	v_add_f32_dpp v59, v57, v56 quad_perm:[1,0,3,2] row_mask:0xf bank_mask:0xf bound_ctrl:1
	v_cndmask_b32_e64 v56, v54, v59, s[10:11]
	v_cndmask_b32_e64 v57, v59, v54, s[10:11]
	s_nop 1
	v_add_f32_dpp v60, v57, v56 quad_perm:[2,3,0,1] row_mask:0xf bank_mask:0xf bound_ctrl:1
	v_cndmask_b32_e64 v56, v51, v60, s[12:13]
	v_cndmask_b32_e64 v57, v60, v51, s[12:13]
	s_nop 1
	v_add_f32_dpp v61, v57, v56 row_shl:4 row_mask:0xf bank_mask:0x5
	s_nop 1
	v_add_f32_dpp v61, v57, v56 row_shr:4 row_mask:0xf bank_mask:0xa
	ds_read_b128 v[160:163], v124 offset:14080
	ds_read_b128 v[164:167], v124 offset:14336
	ds_read_b128 v[168:171], v124 offset:14592
	ds_read_b128 v[172:175], v124 offset:14848
	ds_read_b128 v[176:179], v124 offset:15104
	ds_read_b32 v158, v110 offset:15360
	v_add_f32_dpp v2, v2, v2 row_ror:4 row_mask:0xf bank_mask:0xf bound_ctrl:1
	s_nop 1
	v_add_f32_dpp v2, v2, v2 row_ror:8 row_mask:0xf bank_mask:0xf bound_ctrl:1
	v_pk_fma_f32 v[36:37], v[192:193], v[2:3], v[40:41] op_sel_hi:[1,0,1]
	v_pk_fma_f32 v[38:39], v[194:195], v[2:3], v[42:43] op_sel_hi:[1,0,1]
	s_waitcnt lgkmcnt(11)
	v_mul_f32_e32 v44, v36, v136
	v_mul_f32_e32 v62, v204, v36
	v_fmac_f32_e32 v44, v37, v137
	v_fmac_f32_e32 v62, v37, v205
	v_fmac_f32_e32 v44, v38, v138
	v_fmac_f32_e32 v62, v38, v206
	v_fmac_f32_e32 v44, v39, v139
	v_fmac_f32_e32 v62, v39, v207
	s_waitcnt lgkmcnt(6)
	v_pk_mul_f32 v[40:41], v[148:149], v[156:157] op_sel_hi:[1,0]
	v_pk_mul_f32 v[42:43], v[150:151], v[156:157] op_sel_hi:[1,0]
	v_add_f32_dpp v2, v44, v44 quad_perm:[1,0,3,2] row_mask:0xf bank_mask:0xf bound_ctrl:1
	v_pk_fma_f32 v[40:41], v[36:37], v[144:145], v[40:41]
	v_pk_fma_f32 v[42:43], v[38:39], v[146:147], v[42:43]
	v_add_f32_dpp v2, v2, v2 quad_perm:[2,3,0,1] row_mask:0xf bank_mask:0xf bound_ctrl:1
	ds_read_b128 v[188:191], v124 offset:15488
	ds_read_b128 v[192:195], v124 offset:15744
	ds_read_b128 v[196:199], v124 offset:16000
	ds_read_b128 v[200:203], v124 offset:16256
	ds_read_b128 v[204:207], v124 offset:16512
	ds_read_b32 v208, v110 offset:16768
	s_nop 1
	v_add_f32_dpp v2, v2, v2 row_ror:4 row_mask:0xf bank_mask:0xf bound_ctrl:1
	s_nop 1
	v_add_f32_dpp v2, v2, v2 row_ror:8 row_mask:0xf bank_mask:0xf bound_ctrl:1
	v_pk_fma_f32 v[36:37], v[140:141], v[2:3], v[40:41] op_sel_hi:[1,0,1]
	v_pk_fma_f32 v[38:39], v[142:143], v[2:3], v[42:43] op_sel_hi:[1,0,1]
	s_waitcnt lgkmcnt(11)
	v_mul_f32_e32 v44, v36, v160
	v_mul_f32_e32 v63, v152, v36
	v_fmac_f32_e32 v44, v37, v161
	v_fmac_f32_e32 v63, v37, v153
	v_fmac_f32_e32 v44, v38, v162
	v_fmac_f32_e32 v63, v38, v154
	v_fmac_f32_e32 v44, v39, v163
	v_fmac_f32_e32 v63, v39, v155
	s_waitcnt lgkmcnt(6)
	v_pk_mul_f32 v[40:41], v[172:173], v[158:159] op_sel_hi:[1,0]
	v_pk_mul_f32 v[42:43], v[174:175], v[158:159] op_sel_hi:[1,0]
	v_add_f32_dpp v2, v44, v44 quad_perm:[1,0,3,2] row_mask:0xf bank_mask:0xf bound_ctrl:1
	v_pk_fma_f32 v[40:41], v[36:37], v[168:169], v[40:41]
	v_pk_fma_f32 v[42:43], v[38:39], v[170:171], v[42:43]
	v_add_f32_dpp v2, v2, v2 quad_perm:[2,3,0,1] row_mask:0xf bank_mask:0xf bound_ctrl:1
	v_cndmask_b32_e64 v56, v62, v63, s[8:9]
	v_cndmask_b32_e64 v57, v63, v62, s[8:9]
	s_nop 1
	v_add_f32_dpp v64, v57, v56 quad_perm:[1,0,3,2] row_mask:0xf bank_mask:0xf bound_ctrl:1
	ds_read_b128 v[136:139], v124 offset:16896
	ds_read_b128 v[140:143], v124 offset:17152
	ds_read_b128 v[144:147], v124 offset:17408
	ds_read_b128 v[148:151], v124 offset:17664
	ds_read_b128 v[152:155], v124 offset:17920
	ds_read_b32 v156, v110 offset:18176
	v_add_f32_dpp v2, v2, v2 row_ror:4 row_mask:0xf bank_mask:0xf bound_ctrl:1
	s_nop 1
	v_add_f32_dpp v2, v2, v2 row_ror:8 row_mask:0xf bank_mask:0xf bound_ctrl:1
	v_pk_fma_f32 v[36:37], v[164:165], v[2:3], v[40:41] op_sel_hi:[1,0,1]
	v_pk_fma_f32 v[38:39], v[166:167], v[2:3], v[42:43] op_sel_hi:[1,0,1]
	s_waitcnt lgkmcnt(11)
; #define LAS __attribute__((address_space(3)))
; __device__ __forceinline__ float row16_sum(float x) { x += dpp_mov<0xB1>(x); x += dpp_mov<0x4E>(x); x += dpp_mov<0x124>(x); x += dpp_mov<0x128>(x); return x; }
; __device__ __forceinline__ void scan_phase(const KAS Args& a, LAS unsigned char* lds, int i, const int tid_, const int bid, const int nblk) {
;     ...
;                 for (int t = 0; t < TC; ++t) {
;                     f32x4 kk4n = kk4, nb4n = nb4, w4n = w4, k4n = k4, r4n = r4; float vn = v;
;                     if (t + 1 < TC) { const LAS float* sn = sb + (t + 1) * SST;
;                         kk4n = *(const LAS f32x4*)(sn); nb4n = *(const LAS f32x4*)(sn + 64); w4n = *(const LAS f32x4*)(sn + 128); k4n = *(const LAS f32x4*)(sn + 192); r4n = *(const LAS f32x4*)(sn + 256); vn = vb[(t + 1) * SST]; }
;                     __builtin_amdgcn_sched_barrier(0x6);
;                     float sa = fmaf(S[3], kk4[3], fmaf(S[2], kk4[2], fmaf(S[1], kk4[1], S[0] * kk4[0])));
;                     const f32x4 Tm = S * w4 + k4 * v;
;                     sa = row16_sum(sa);
;                     S = Tm + nb4 * sa;
;                     float y = fmaf(S[3], r4[3], fmaf(S[2], r4[2], fmaf(S[1], r4[1], S[0] * r4[0]))); y = row16_sum(y);
;                     ysel = (cgp == (t & 15)) ? y : ysel;
;                     if ((t & 15) == 15) yb[(t - 15 + cgp) * 32 + rl] = ysel;
;                     kk4 = kk4n; nb4 = nb4n; w4 = w4n; k4 = k4n; r4 = r4n; v = vn; }
	v_mul_f32_e32 v44, v36, v188
	v_mul_f32_e32 v65, v176, v36
	v_fmac_f32_e32 v44, v37, v189
	v_fmac_f32_e32 v65, v37, v177
	v_fmac_f32_e32 v44, v38, v190
	v_fmac_f32_e32 v65, v38, v178
	v_fmac_f32_e32 v44, v39, v191
	v_fmac_f32_e32 v65, v39, v179
	s_waitcnt lgkmcnt(6)
	v_pk_mul_f32 v[40:41], v[200:201], v[208:209] op_sel_hi:[1,0]
	v_pk_mul_f32 v[42:43], v[202:203], v[208:209] op_sel_hi:[1,0]
	v_add_f32_dpp v2, v44, v44 quad_perm:[1,0,3,2] row_mask:0xf bank_mask:0xf bound_ctrl:1
	v_pk_fma_f32 v[40:41], v[36:37], v[196:197], v[40:41]
	v_pk_fma_f32 v[42:43], v[38:39], v[198:199], v[42:43]
	v_add_f32_dpp v2, v2, v2 quad_perm:[2,3,0,1] row_mask:0xf bank_mask:0xf bound_ctrl:1
	ds_read_b128 v[160:163], v124 offset:18304
	ds_read_b128 v[164:167], v124 offset:18560
	ds_read_b128 v[168:171], v124 offset:18816
	ds_read_b128 v[172:175], v124 offset:19072
	ds_read_b128 v[176:179], v124 offset:19328
	ds_read_b32 v158, v110 offset:19584
	s_nop 1
	v_add_f32_dpp v2, v2, v2 row_ror:4 row_mask:0xf bank_mask:0xf bound_ctrl:1
	s_nop 1
	v_add_f32_dpp v2, v2, v2 row_ror:8 row_mask:0xf bank_mask:0xf bound_ctrl:1
	v_pk_fma_f32 v[36:37], v[192:193], v[2:3], v[40:41] op_sel_hi:[1,0,1]
	v_pk_fma_f32 v[38:39], v[194:195], v[2:3], v[42:43] op_sel_hi:[1,0,1]
	s_waitcnt lgkmcnt(11)
	v_mul_f32_e32 v44, v36, v136
	v_mul_f32_e32 v66, v204, v36
	v_fmac_f32_e32 v44, v37, v137
	v_fmac_f32_e32 v66, v37, v205
	v_fmac_f32_e32 v44, v38, v138
	v_fmac_f32_e32 v66, v38, v206
	v_fmac_f32_e32 v44, v39, v139
	v_fmac_f32_e32 v66, v39, v207
	s_waitcnt lgkmcnt(6)
	v_pk_mul_f32 v[40:41], v[148:149], v[156:157] op_sel_hi:[1,0]
	v_pk_mul_f32 v[42:43], v[150:151], v[156:157] op_sel_hi:[1,0]
	v_add_f32_dpp v2, v44, v44 quad_perm:[1,0,3,2] row_mask:0xf bank_mask:0xf bound_ctrl:1
	v_pk_fma_f32 v[40:41], v[36:37], v[144:145], v[40:41]
	v_pk_fma_f32 v[42:43], v[38:39], v[146:147], v[42:43]
	v_add_f32_dpp v2, v2, v2 quad_perm:[2,3,0,1] row_mask:0xf bank_mask:0xf bound_ctrl:1
	v_cndmask_b32_e64 v56, v65, v66, s[8:9]
	v_cndmask_b32_e64 v57, v66, v65, s[8:9]
	s_nop 1
	v_add_f32_dpp v67, v57, v56 quad_perm:[1,0,3,2] row_mask:0xf bank_mask:0xf bound_ctrl:1
	v_cndmask_b32_e64 v56, v64, v67, s[10:11]
	v_cndmask_b32_e64 v57, v67, v64, s[10:11]
	s_nop 1
	v_add_f32_dpp v45, v57, v56 quad_perm:[2,3,0,1] row_mask:0xf bank_mask:0xf bound_ctrl:1
	ds_read_b128 v[188:191], v124 offset:19712
	ds_read_b128 v[192:195], v124 offset:19968
	ds_read_b128 v[196:199], v124 offset:20224
	ds_read_b128 v[200:203], v124 offset:20480
	ds_read_b128 v[204:207], v124 offset:20736
	ds_read_b32 v208, v110 offset:20992
	v_add_f32_dpp v2, v2, v2 row_ror:4 row_mask:0xf bank_mask:0xf bound_ctrl:1
	s_nop 1
	v_add_f32_dpp v2, v2, v2 row_ror:8 row_mask:0xf bank_mask:0xf bound_ctrl:1
	v_pk_fma_f32 v[36:37], v[140:141], v[2:3], v[40:41] op_sel_hi:[1,0,1]
	v_pk_fma_f32 v[38:39], v[142:143], v[2:3], v[42:43] op_sel_hi:[1,0,1]
	s_waitcnt lgkmcnt(11)
	v_mul_f32_e32 v44, v36, v160
	v_mul_f32_e32 v46, v152, v36
	v_fmac_f32_e32 v44, v37, v161
	v_fmac_f32_e32 v46, v37, v153
	v_fmac_f32_e32 v44, v38, v162
	v_fmac_f32_e32 v46, v38, v154
	v_fmac_f32_e32 v44, v39, v163
	v_fmac_f32_e32 v46, v39, v155
	s_waitcnt lgkmcnt(6)
	v_pk_mul_f32 v[40:41], v[172:173], v[158:159] op_sel_hi:[1,0]
	v_pk_mul_f32 v[42:43], v[174:175], v[158:159] op_sel_hi:[1,0]
	v_add_f32_dpp v2, v44, v44 quad_perm:[1,0,3,2] row_mask:0xf bank_mask:0xf bound_ctrl:1
	v_pk_fma_f32 v[40:41], v[36:37], v[168:169], v[40:41]
	v_pk_fma_f32 v[42:43], v[38:39], v[170:171], v[42:43]
	v_add_f32_dpp v2, v2, v2 quad_perm:[2,3,0,1] row_mask:0xf bank_mask:0xf bound_ctrl:1
	ds_read_b128 v[136:139], v124 offset:21120
	ds_read_b128 v[140:143], v124 offset:21376
	ds_read_b128 v[144:147], v124 offset:21632
	ds_read_b128 v[148:151], v124 offset:21888
	ds_read_b128 v[152:155], v124 offset:22144
	ds_read_b32 v156, v110 offset:22400
	s_nop 1
	v_add_f32_dpp v2, v2, v2 row_ror:4 row_mask:0xf bank_mask:0xf bound_ctrl:1
	s_nop 1
	v_add_f32_dpp v2, v2, v2 row_ror:8 row_mask:0xf bank_mask:0xf bound_ctrl:1
	v_pk_fma_f32 v[36:37], v[164:165], v[2:3], v[40:41] op_sel_hi:[1,0,1]
	v_pk_fma_f32 v[38:39], v[166:167], v[2:3], v[42:43] op_sel_hi:[1,0,1]
	s_waitcnt lgkmcnt(11)
	v_mul_f32_e32 v44, v36, v188
	v_mul_f32_e32 v48, v176, v36
	v_fmac_f32_e32 v44, v37, v189
	v_fmac_f32_e32 v48, v37, v177
	v_fmac_f32_e32 v44, v38, v190
	v_fmac_f32_e32 v48, v38, v178
	v_fmac_f32_e32 v44, v39, v191
	v_fmac_f32_e32 v48, v39, v179
	s_waitcnt lgkmcnt(6)
	v_pk_mul_f32 v[40:41], v[200:201], v[208:209] op_sel_hi:[1,0]
	v_pk_mul_f32 v[42:43], v[202:203], v[208:209] op_sel_hi:[1,0]
	v_add_f32_dpp v2, v44, v44 quad_perm:[1,0,3,2] row_mask:0xf bank_mask:0xf bound_ctrl:1
	v_pk_fma_f32 v[40:41], v[36:37], v[196:197], v[40:41]
	v_pk_fma_f32 v[42:43], v[38:39], v[198:199], v[42:43]
	v_add_f32_dpp v2, v2, v2 quad_perm:[2,3,0,1] row_mask:0xf bank_mask:0xf bound_ctrl:1
	v_cndmask_b32_e64 v56, v46, v48, s[8:9]
	v_cndmask_b32_e64 v57, v48, v46, s[8:9]
	s_nop 1
	v_add_f32_dpp v49, v57, v56 quad_perm:[1,0,3,2] row_mask:0xf bank_mask:0xf bound_ctrl:1
	ds_read_b128 v[160:163], v124 offset:22528
	ds_read_b128 v[164:167], v124 offset:22784
	ds_read_b128 v[168:171], v124 offset:23040
	ds_read_b128 v[172:175], v124 offset:23296
	ds_read_b128 v[176:179], v124 offset:23552
	ds_read_b32 v158, v110 offset:23808
	v_add_f32_dpp v2, v2, v2 row_ror:4 row_mask:0xf bank_mask:0xf bound_ctrl:1
	s_nop 1
	v_add_f32_dpp v2, v2, v2 row_ror:8 row_mask:0xf bank_mask:0xf bound_ctrl:1
	v_pk_fma_f32 v[36:37], v[192:193], v[2:3], v[40:41] op_sel_hi:[1,0,1]
	v_pk_fma_f32 v[38:39], v[194:195], v[2:3], v[42:43] op_sel_hi:[1,0,1]
	s_waitcnt lgkmcnt(11)
; #define LAS __attribute__((address_space(3)))
; __device__ __forceinline__ float row16_sum(float x) { x += dpp_mov<0xB1>(x); x += dpp_mov<0x4E>(x); x += dpp_mov<0x124>(x); x += dpp_mov<0x128>(x); return x; }
; __device__ __forceinline__ void scan_phase(const KAS Args& a, LAS unsigned char* lds, int i, const int tid_, const int bid, const int nblk) {
;     ...
;                 for (int t = 0; t < TC; ++t) {
;                     f32x4 kk4n = kk4, nb4n = nb4, w4n = w4, k4n = k4, r4n = r4; float vn = v;
;                     if (t + 1 < TC) { const LAS float* sn = sb + (t + 1) * SST;
;                         kk4n = *(const LAS f32x4*)(sn); nb4n = *(const LAS f32x4*)(sn + 64); w4n = *(const LAS f32x4*)(sn + 128); k4n = *(const LAS f32x4*)(sn + 192); r4n = *(const LAS f32x4*)(sn + 256); vn = vb[(t + 1) * SST]; }
;                     __builtin_amdgcn_sched_barrier(0x6);
;                     float sa = fmaf(S[3], kk4[3], fmaf(S[2], kk4[2], fmaf(S[1], kk4[1], S[0] * kk4[0])));
;                     const f32x4 Tm = S * w4 + k4 * v;
;                     sa = row16_sum(sa);
;                     S = Tm + nb4 * sa;
;                     float y = fmaf(S[3], r4[3], fmaf(S[2], r4[2], fmaf(S[1], r4[1], S[0] * r4[0]))); y = row16_sum(y);
;                     ysel = (cgp == (t & 15)) ? y : ysel;
;                     if ((t & 15) == 15) yb[(t - 15 + cgp) * 32 + rl] = ysel;
;                     kk4 = kk4n; nb4 = nb4n; w4 = w4n; k4 = k4n; r4 = r4n; v = vn; }
	v_mul_f32_e32 v44, v36, v136
	v_mul_f32_e32 v47, v204, v36
	v_fmac_f32_e32 v44, v37, v137
	v_fmac_f32_e32 v47, v37, v205
	v_fmac_f32_e32 v44, v38, v138
	v_fmac_f32_e32 v47, v38, v206
	v_fmac_f32_e32 v44, v39, v139
	v_fmac_f32_e32 v47, v39, v207
	s_waitcnt lgkmcnt(6)
	v_pk_mul_f32 v[40:41], v[148:149], v[156:157] op_sel_hi:[1,0]
	v_pk_mul_f32 v[42:43], v[150:151], v[156:157] op_sel_hi:[1,0]
	v_add_f32_dpp v2, v44, v44 quad_perm:[1,0,3,2] row_mask:0xf bank_mask:0xf bound_ctrl:1
	v_pk_fma_f32 v[40:41], v[36:37], v[144:145], v[40:41]
	v_pk_fma_f32 v[42:43], v[38:39], v[146:147], v[42:43]
	v_add_f32_dpp v2, v2, v2 quad_perm:[2,3,0,1] row_mask:0xf bank_mask:0xf bound_ctrl:1
	ds_read_b128 v[188:191], v124 offset:23936
	ds_read_b128 v[192:195], v124 offset:24192
	ds_read_b128 v[196:199], v124 offset:24448
	ds_read_b128 v[200:203], v124 offset:24704
	ds_read_b128 v[204:207], v124 offset:24960
	ds_read_b32 v208, v110 offset:25216
	s_nop 1
	v_add_f32_dpp v2, v2, v2 row_ror:4 row_mask:0xf bank_mask:0xf bound_ctrl:1
	s_nop 1
	v_add_f32_dpp v2, v2, v2 row_ror:8 row_mask:0xf bank_mask:0xf bound_ctrl:1
	v_pk_fma_f32 v[36:37], v[140:141], v[2:3], v[40:41] op_sel_hi:[1,0,1]
	v_pk_fma_f32 v[38:39], v[142:143], v[2:3], v[42:43] op_sel_hi:[1,0,1]
	s_waitcnt lgkmcnt(11)
	v_mul_f32_e32 v44, v36, v160
	v_mul_f32_e32 v50, v152, v36
	v_fmac_f32_e32 v44, v37, v161
	v_fmac_f32_e32 v50, v37, v153
	v_fmac_f32_e32 v44, v38, v162
	v_fmac_f32_e32 v50, v38, v154
	v_fmac_f32_e32 v44, v39, v163
	v_fmac_f32_e32 v50, v39, v155
	s_waitcnt lgkmcnt(6)
	v_pk_mul_f32 v[40:41], v[172:173], v[158:159] op_sel_hi:[1,0]
	v_pk_mul_f32 v[42:43], v[174:175], v[158:159] op_sel_hi:[1,0]
	v_add_f32_dpp v2, v44, v44 quad_perm:[1,0,3,2] row_mask:0xf bank_mask:0xf bound_ctrl:1
	v_pk_fma_f32 v[40:41], v[36:37], v[168:169], v[40:41]
	v_pk_fma_f32 v[42:43], v[38:39], v[170:171], v[42:43]
	v_add_f32_dpp v2, v2, v2 quad_perm:[2,3,0,1] row_mask:0xf bank_mask:0xf bound_ctrl:1
	v_cndmask_b32_e64 v56, v47, v50, s[8:9]
	v_cndmask_b32_e64 v57, v50, v47, s[8:9]
	s_nop 1
	v_add_f32_dpp v52, v57, v56 quad_perm:[1,0,3,2] row_mask:0xf bank_mask:0xf bound_ctrl:1
	v_cndmask_b32_e64 v56, v49, v52, s[10:11]
	v_cndmask_b32_e64 v57, v52, v49, s[10:11]
	s_nop 1
	v_add_f32_dpp v53, v57, v56 quad_perm:[2,3,0,1] row_mask:0xf bank_mask:0xf bound_ctrl:1
	v_cndmask_b32_e64 v56, v45, v53, s[12:13]
	v_cndmask_b32_e64 v57, v53, v45, s[12:13]
	s_nop 1
	v_add_f32_dpp v55, v57, v56 row_shl:4 row_mask:0xf bank_mask:0x5
	s_nop 1
	v_add_f32_dpp v55, v57, v56 row_shr:4 row_mask:0xf bank_mask:0xa
	v_cndmask_b32_e64 v56, v61, v55, s[14:15]
	v_cndmask_b32_e64 v57, v55, v61, s[14:15]
	s_nop 1
	v_add_f32_dpp v58, v57, v56 row_ror:8 row_mask:0xf bank_mask:0xf bound_ctrl:1
	ds_read_b128 v[136:139], v124 offset:25344
	ds_read_b128 v[140:143], v124 offset:25600
	ds_read_b128 v[144:147], v124 offset:25856
	ds_read_b128 v[148:151], v124 offset:26112
	ds_read_b128 v[152:155], v124 offset:26368
	ds_read_b32 v156, v110 offset:26624
	v_add_f32_dpp v2, v2, v2 row_ror:4 row_mask:0xf bank_mask:0xf bound_ctrl:1
	s_nop 1
	v_add_f32_dpp v2, v2, v2 row_ror:8 row_mask:0xf bank_mask:0xf bound_ctrl:1
	ds_write_b32 v122, v58
	v_pk_fma_f32 v[36:37], v[164:165], v[2:3], v[40:41] op_sel_hi:[1,0,1]
	v_pk_fma_f32 v[38:39], v[166:167], v[2:3], v[42:43] op_sel_hi:[1,0,1]
	s_waitcnt lgkmcnt(12)
	v_mul_f32_e32 v44, v36, v188
	v_mul_f32_e32 v54, v176, v36
	v_fmac_f32_e32 v44, v37, v189
	v_fmac_f32_e32 v54, v37, v177
	v_fmac_f32_e32 v44, v38, v190
	v_fmac_f32_e32 v54, v38, v178
	v_fmac_f32_e32 v44, v39, v191
	v_fmac_f32_e32 v54, v39, v179
	s_waitcnt lgkmcnt(7)
	v_pk_mul_f32 v[40:41], v[200:201], v[208:209] op_sel_hi:[1,0]
	v_pk_mul_f32 v[42:43], v[202:203], v[208:209] op_sel_hi:[1,0]
	v_add_f32_dpp v2, v44, v44 quad_perm:[1,0,3,2] row_mask:0xf bank_mask:0xf bound_ctrl:1
	v_pk_fma_f32 v[40:41], v[36:37], v[196:197], v[40:41]
	v_pk_fma_f32 v[42:43], v[38:39], v[198:199], v[42:43]
	v_add_f32_dpp v2, v2, v2 quad_perm:[2,3,0,1] row_mask:0xf bank_mask:0xf bound_ctrl:1
	ds_read_b128 v[160:163], v124 offset:26752
	ds_read_b128 v[164:167], v124 offset:27008
	ds_read_b128 v[168:171], v124 offset:27264
	ds_read_b128 v[172:175], v124 offset:27520
	ds_read_b128 v[176:179], v124 offset:27776
	ds_read_b32 v158, v110 offset:28032
	s_nop 1
	v_add_f32_dpp v2, v2, v2 row_ror:4 row_mask:0xf bank_mask:0xf bound_ctrl:1
	s_nop 1
	v_add_f32_dpp v2, v2, v2 row_ror:8 row_mask:0xf bank_mask:0xf bound_ctrl:1
	v_pk_fma_f32 v[36:37], v[192:193], v[2:3], v[40:41] op_sel_hi:[1,0,1]
	v_pk_fma_f32 v[38:39], v[194:195], v[2:3], v[42:43] op_sel_hi:[1,0,1]
	s_waitcnt lgkmcnt(12)
	v_mul_f32_e32 v44, v36, v136
	v_mul_f32_e32 v59, v204, v36
	v_fmac_f32_e32 v44, v37, v137
	v_fmac_f32_e32 v59, v37, v205
	v_fmac_f32_e32 v44, v38, v138
	v_fmac_f32_e32 v59, v38, v206
	v_fmac_f32_e32 v44, v39, v139
	v_fmac_f32_e32 v59, v39, v207
	s_waitcnt lgkmcnt(7)
	v_pk_mul_f32 v[40:41], v[148:149], v[156:157] op_sel_hi:[1,0]
	v_pk_mul_f32 v[42:43], v[150:151], v[156:157] op_sel_hi:[1,0]
	v_add_f32_dpp v2, v44, v44 quad_perm:[1,0,3,2] row_mask:0xf bank_mask:0xf bound_ctrl:1
	v_pk_fma_f32 v[40:41], v[36:37], v[144:145], v[40:41]
	v_pk_fma_f32 v[42:43], v[38:39], v[146:147], v[42:43]
	v_add_f32_dpp v2, v2, v2 quad_perm:[2,3,0,1] row_mask:0xf bank_mask:0xf bound_ctrl:1
	v_cndmask_b32_e64 v56, v54, v59, s[8:9]
	v_cndmask_b32_e64 v57, v59, v54, s[8:9]
	s_nop 1
	v_add_f32_dpp v51, v57, v56 quad_perm:[1,0,3,2] row_mask:0xf bank_mask:0xf bound_ctrl:1
	ds_read_b128 v[188:191], v124 offset:28160
	ds_read_b128 v[192:195], v124 offset:28416
	ds_read_b128 v[196:199], v124 offset:28672
	ds_read_b128 v[200:203], v124 offset:28928
	ds_read_b128 v[204:207], v124 offset:29184
	ds_read_b32 v208, v110 offset:29440
	v_add_f32_dpp v2, v2, v2 row_ror:4 row_mask:0xf bank_mask:0xf bound_ctrl:1
	s_nop 1
	v_add_f32_dpp v2, v2, v2 row_ror:8 row_mask:0xf bank_mask:0xf bound_ctrl:1
	v_pk_fma_f32 v[36:37], v[140:141], v[2:3], v[40:41] op_sel_hi:[1,0,1]
	v_pk_fma_f32 v[38:39], v[142:143], v[2:3], v[42:43] op_sel_hi:[1,0,1]
	s_waitcnt lgkmcnt(11)
; #define LAS __attribute__((address_space(3)))
; __device__ __forceinline__ float row16_sum(float x) { x += dpp_mov<0xB1>(x); x += dpp_mov<0x4E>(x); x += dpp_mov<0x124>(x); x += dpp_mov<0x128>(x); return x; }
; __device__ __forceinline__ void scan_phase(const KAS Args& a, LAS unsigned char* lds, int i, const int tid_, const int bid, const int nblk) {
;     ...
;                 for (int t = 0; t < TC; ++t) {
;                     f32x4 kk4n = kk4, nb4n = nb4, w4n = w4, k4n = k4, r4n = r4; float vn = v;
;                     if (t + 1 < TC) { const LAS float* sn = sb + (t + 1) * SST;
;                         kk4n = *(const LAS f32x4*)(sn); nb4n = *(const LAS f32x4*)(sn + 64); w4n = *(const LAS f32x4*)(sn + 128); k4n = *(const LAS f32x4*)(sn + 192); r4n = *(const LAS f32x4*)(sn + 256); vn = vb[(t + 1) * SST]; }
;                     __builtin_amdgcn_sched_barrier(0x6);
;                     float sa = fmaf(S[3], kk4[3], fmaf(S[2], kk4[2], fmaf(S[1], kk4[1], S[0] * kk4[0])));
;                     const f32x4 Tm = S * w4 + k4 * v;
;                     sa = row16_sum(sa);
;                     S = Tm + nb4 * sa;
;                     float y = fmaf(S[3], r4[3], fmaf(S[2], r4[2], fmaf(S[1], r4[1], S[0] * r4[0]))); y = row16_sum(y);
;                     ysel = (cgp == (t & 15)) ? y : ysel;
;                     if ((t & 15) == 15) yb[(t - 15 + cgp) * 32 + rl] = ysel;
;                     kk4 = kk4n; nb4 = nb4n; w4 = w4n; k4 = k4n; r4 = r4n; v = vn; }
	v_mul_f32_e32 v44, v36, v160
	v_mul_f32_e32 v60, v152, v36
	v_fmac_f32_e32 v44, v37, v161
	v_fmac_f32_e32 v60, v37, v153
	v_fmac_f32_e32 v44, v38, v162
	v_fmac_f32_e32 v60, v38, v154
	v_fmac_f32_e32 v44, v39, v163
	v_fmac_f32_e32 v60, v39, v155
	s_waitcnt lgkmcnt(6)
	v_pk_mul_f32 v[40:41], v[172:173], v[158:159] op_sel_hi:[1,0]
	v_pk_mul_f32 v[42:43], v[174:175], v[158:159] op_sel_hi:[1,0]
	v_add_f32_dpp v2, v44, v44 quad_perm:[1,0,3,2] row_mask:0xf bank_mask:0xf bound_ctrl:1
	v_pk_fma_f32 v[40:41], v[36:37], v[168:169], v[40:41]
	v_pk_fma_f32 v[42:43], v[38:39], v[170:171], v[42:43]
	v_add_f32_dpp v2, v2, v2 quad_perm:[2,3,0,1] row_mask:0xf bank_mask:0xf bound_ctrl:1
	ds_read_b128 v[136:139], v124 offset:29568
	ds_read_b128 v[140:143], v124 offset:29824
	ds_read_b128 v[144:147], v124 offset:30080
	ds_read_b128 v[148:151], v124 offset:30336
	ds_read_b128 v[152:155], v124 offset:30592
	ds_read_b32 v156, v110 offset:30848
	s_nop 1
	v_add_f32_dpp v2, v2, v2 row_ror:4 row_mask:0xf bank_mask:0xf bound_ctrl:1
	s_nop 1
	v_add_f32_dpp v2, v2, v2 row_ror:8 row_mask:0xf bank_mask:0xf bound_ctrl:1
	v_pk_fma_f32 v[36:37], v[164:165], v[2:3], v[40:41] op_sel_hi:[1,0,1]
	v_pk_fma_f32 v[38:39], v[166:167], v[2:3], v[42:43] op_sel_hi:[1,0,1]
	s_waitcnt lgkmcnt(11)
	v_mul_f32_e32 v44, v36, v188
	v_mul_f32_e32 v62, v176, v36
	v_fmac_f32_e32 v44, v37, v189
	v_fmac_f32_e32 v62, v37, v177
	v_fmac_f32_e32 v44, v38, v190
	v_fmac_f32_e32 v62, v38, v178
	v_fmac_f32_e32 v44, v39, v191
	v_fmac_f32_e32 v62, v39, v179
	s_waitcnt lgkmcnt(6)
	v_pk_mul_f32 v[40:41], v[200:201], v[208:209] op_sel_hi:[1,0]
	v_pk_mul_f32 v[42:43], v[202:203], v[208:209] op_sel_hi:[1,0]
	v_add_f32_dpp v2, v44, v44 quad_perm:[1,0,3,2] row_mask:0xf bank_mask:0xf bound_ctrl:1
	v_pk_fma_f32 v[40:41], v[36:37], v[196:197], v[40:41]
	v_pk_fma_f32 v[42:43], v[38:39], v[198:199], v[42:43]
	v_add_f32_dpp v2, v2, v2 quad_perm:[2,3,0,1] row_mask:0xf bank_mask:0xf bound_ctrl:1
	v_cndmask_b32_e64 v56, v60, v62, s[8:9]
	v_cndmask_b32_e64 v57, v62, v60, s[8:9]
	s_nop 1
	v_add_f32_dpp v63, v57, v56 quad_perm:[1,0,3,2] row_mask:0xf bank_mask:0xf bound_ctrl:1
	v_cndmask_b32_e64 v56, v51, v63, s[10:11]
	v_cndmask_b32_e64 v57, v63, v51, s[10:11]
	s_nop 1
	v_add_f32_dpp v65, v57, v56 quad_perm:[2,3,0,1] row_mask:0xf bank_mask:0xf bound_ctrl:1
	ds_read_b128 v[160:163], v124 offset:30976
	ds_read_b128 v[164:167], v124 offset:31232
	ds_read_b128 v[168:171], v124 offset:31488
	ds_read_b128 v[172:175], v124 offset:31744
	ds_read_b128 v[176:179], v124 offset:32000
	ds_read_b32 v158, v110 offset:32256
	v_add_f32_dpp v2, v2, v2 row_ror:4 row_mask:0xf bank_mask:0xf bound_ctrl:1
	s_nop 1
	v_add_f32_dpp v2, v2, v2 row_ror:8 row_mask:0xf bank_mask:0xf bound_ctrl:1
	v_pk_fma_f32 v[36:37], v[192:193], v[2:3], v[40:41] op_sel_hi:[1,0,1]
	v_pk_fma_f32 v[38:39], v[194:195], v[2:3], v[42:43] op_sel_hi:[1,0,1]
	s_waitcnt lgkmcnt(11)
	v_mul_f32_e32 v44, v36, v136
	v_mul_f32_e32 v66, v204, v36
	v_fmac_f32_e32 v44, v37, v137
	v_fmac_f32_e32 v66, v37, v205
	v_fmac_f32_e32 v44, v38, v138
	v_fmac_f32_e32 v66, v38, v206
	v_fmac_f32_e32 v44, v39, v139
	v_fmac_f32_e32 v66, v39, v207
	s_waitcnt lgkmcnt(6)
	v_pk_mul_f32 v[40:41], v[148:149], v[156:157] op_sel_hi:[1,0]
	v_pk_mul_f32 v[42:43], v[150:151], v[156:157] op_sel_hi:[1,0]
	v_add_f32_dpp v2, v44, v44 quad_perm:[1,0,3,2] row_mask:0xf bank_mask:0xf bound_ctrl:1
	v_pk_fma_f32 v[40:41], v[36:37], v[144:145], v[40:41]
	v_pk_fma_f32 v[42:43], v[38:39], v[146:147], v[42:43]
	v_add_f32_dpp v2, v2, v2 quad_perm:[2,3,0,1] row_mask:0xf bank_mask:0xf bound_ctrl:1
	ds_read_b128 v[188:191], v124 offset:32384
	ds_read_b128 v[192:195], v124 offset:32640
	ds_read_b128 v[196:199], v124 offset:32896
	ds_read_b128 v[200:203], v124 offset:33152
	ds_read_b128 v[204:207], v124 offset:33408
	ds_read_b32 v208, v110 offset:33664
	s_nop 1
	v_add_f32_dpp v2, v2, v2 row_ror:4 row_mask:0xf bank_mask:0xf bound_ctrl:1
	s_nop 1
	v_add_f32_dpp v2, v2, v2 row_ror:8 row_mask:0xf bank_mask:0xf bound_ctrl:1
	v_pk_fma_f32 v[36:37], v[140:141], v[2:3], v[40:41] op_sel_hi:[1,0,1]
	v_pk_fma_f32 v[38:39], v[142:143], v[2:3], v[42:43] op_sel_hi:[1,0,1]
	s_waitcnt lgkmcnt(11)
	v_mul_f32_e32 v44, v36, v160
	v_mul_f32_e32 v64, v152, v36
	v_fmac_f32_e32 v44, v37, v161
	v_fmac_f32_e32 v64, v37, v153
	v_fmac_f32_e32 v44, v38, v162
	v_fmac_f32_e32 v64, v38, v154
	v_fmac_f32_e32 v44, v39, v163
	v_fmac_f32_e32 v64, v39, v155
	s_waitcnt lgkmcnt(6)
	v_pk_mul_f32 v[40:41], v[172:173], v[158:159] op_sel_hi:[1,0]
	v_pk_mul_f32 v[42:43], v[174:175], v[158:159] op_sel_hi:[1,0]
	v_add_f32_dpp v2, v44, v44 quad_perm:[1,0,3,2] row_mask:0xf bank_mask:0xf bound_ctrl:1
	v_pk_fma_f32 v[40:41], v[36:37], v[168:169], v[40:41]
	v_pk_fma_f32 v[42:43], v[38:39], v[170:171], v[42:43]
	v_add_f32_dpp v2, v2, v2 quad_perm:[2,3,0,1] row_mask:0xf bank_mask:0xf bound_ctrl:1
	v_cndmask_b32_e64 v56, v66, v64, s[8:9]
	v_cndmask_b32_e64 v57, v64, v66, s[8:9]
	s_nop 1
	v_add_f32_dpp v67, v57, v56 quad_perm:[1,0,3,2] row_mask:0xf bank_mask:0xf bound_ctrl:1
	ds_read_b128 v[136:139], v124 offset:33792
	ds_read_b128 v[140:143], v124 offset:34048
	ds_read_b128 v[144:147], v124 offset:34304
	ds_read_b128 v[148:151], v124 offset:34560
	ds_read_b128 v[152:155], v124 offset:34816
	ds_read_b32 v156, v110 offset:35072
	v_add_f32_dpp v2, v2, v2 row_ror:4 row_mask:0xf bank_mask:0xf bound_ctrl:1
	s_nop 1
	v_add_f32_dpp v2, v2, v2 row_ror:8 row_mask:0xf bank_mask:0xf bound_ctrl:1
	v_pk_fma_f32 v[36:37], v[164:165], v[2:3], v[40:41] op_sel_hi:[1,0,1]
	v_pk_fma_f32 v[38:39], v[166:167], v[2:3], v[42:43] op_sel_hi:[1,0,1]
	s_waitcnt lgkmcnt(11)
; #define LAS __attribute__((address_space(3)))
; __device__ __forceinline__ float row16_sum(float x) { x += dpp_mov<0xB1>(x); x += dpp_mov<0x4E>(x); x += dpp_mov<0x124>(x); x += dpp_mov<0x128>(x); return x; }
; __device__ __forceinline__ void scan_phase(const KAS Args& a, LAS unsigned char* lds, int i, const int tid_, const int bid, const int nblk) {
;     ...
;                 for (int t = 0; t < TC; ++t) {
;                     f32x4 kk4n = kk4, nb4n = nb4, w4n = w4, k4n = k4, r4n = r4; float vn = v;
;                     if (t + 1 < TC) { const LAS float* sn = sb + (t + 1) * SST;
;                         kk4n = *(const LAS f32x4*)(sn); nb4n = *(const LAS f32x4*)(sn + 64); w4n = *(const LAS f32x4*)(sn + 128); k4n = *(const LAS f32x4*)(sn + 192); r4n = *(const LAS f32x4*)(sn + 256); vn = vb[(t + 1) * SST]; }
;                     __builtin_amdgcn_sched_barrier(0x6);
;                     float sa = fmaf(S[3], kk4[3], fmaf(S[2], kk4[2], fmaf(S[1], kk4[1], S[0] * kk4[0])));
;                     const f32x4 Tm = S * w4 + k4 * v;
;                     sa = row16_sum(sa);
;                     S = Tm + nb4 * sa;
;                     float y = fmaf(S[3], r4[3], fmaf(S[2], r4[2], fmaf(S[1], r4[1], S[0] * r4[0]))); y = row16_sum(y);
;                     ysel = (cgp == (t & 15)) ? y : ysel;
;                     if ((t & 15) == 15) yb[(t - 15 + cgp) * 32 + rl] = ysel;
;                     kk4 = kk4n; nb4 = nb4n; w4 = w4n; k4 = k4n; r4 = r4n; v = vn; }
	v_mul_f32_e32 v44, v36, v188
	v_mul_f32_e32 v46, v176, v36
	v_fmac_f32_e32 v44, v37, v189
	v_fmac_f32_e32 v46, v37, v177
	v_fmac_f32_e32 v44, v38, v190
	v_fmac_f32_e32 v46, v38, v178
	v_fmac_f32_e32 v44, v39, v191
	v_fmac_f32_e32 v46, v39, v179
	s_waitcnt lgkmcnt(6)
	v_pk_mul_f32 v[40:41], v[200:201], v[208:209] op_sel_hi:[1,0]
	v_pk_mul_f32 v[42:43], v[202:203], v[208:209] op_sel_hi:[1,0]
	v_add_f32_dpp v2, v44, v44 quad_perm:[1,0,3,2] row_mask:0xf bank_mask:0xf bound_ctrl:1
	v_pk_fma_f32 v[40:41], v[36:37], v[196:197], v[40:41]
	v_pk_fma_f32 v[42:43], v[38:39], v[198:199], v[42:43]
	v_add_f32_dpp v2, v2, v2 quad_perm:[2,3,0,1] row_mask:0xf bank_mask:0xf bound_ctrl:1
	ds_read_b128 v[160:163], v124 offset:35200
	ds_read_b128 v[164:167], v124 offset:35456
	ds_read_b128 v[168:171], v124 offset:35712
	ds_read_b128 v[172:175], v124 offset:35968
	ds_read_b128 v[176:179], v124 offset:36224
	ds_read_b32 v158, v110 offset:36480
	s_nop 1
	v_add_f32_dpp v2, v2, v2 row_ror:4 row_mask:0xf bank_mask:0xf bound_ctrl:1
	s_nop 1
	v_add_f32_dpp v2, v2, v2 row_ror:8 row_mask:0xf bank_mask:0xf bound_ctrl:1
	v_pk_fma_f32 v[36:37], v[192:193], v[2:3], v[40:41] op_sel_hi:[1,0,1]
	v_pk_fma_f32 v[38:39], v[194:195], v[2:3], v[42:43] op_sel_hi:[1,0,1]
	s_waitcnt lgkmcnt(11)
	v_mul_f32_e32 v44, v36, v136
	v_mul_f32_e32 v48, v204, v36
	v_fmac_f32_e32 v44, v37, v137
	v_fmac_f32_e32 v48, v37, v205
	v_fmac_f32_e32 v44, v38, v138
	v_fmac_f32_e32 v48, v38, v206
	v_fmac_f32_e32 v44, v39, v139
	v_fmac_f32_e32 v48, v39, v207
	s_waitcnt lgkmcnt(6)
	v_pk_mul_f32 v[40:41], v[148:149], v[156:157] op_sel_hi:[1,0]
	v_pk_mul_f32 v[42:43], v[150:151], v[156:157] op_sel_hi:[1,0]
	v_add_f32_dpp v2, v44, v44 quad_perm:[1,0,3,2] row_mask:0xf bank_mask:0xf bound_ctrl:1
	v_pk_fma_f32 v[40:41], v[36:37], v[144:145], v[40:41]
	v_pk_fma_f32 v[42:43], v[38:39], v[146:147], v[42:43]
	v_add_f32_dpp v2, v2, v2 quad_perm:[2,3,0,1] row_mask:0xf bank_mask:0xf bound_ctrl:1
	v_cndmask_b32_e64 v56, v46, v48, s[8:9]
	v_cndmask_b32_e64 v57, v48, v46, s[8:9]
	s_nop 1
	v_add_f32_dpp v47, v57, v56 quad_perm:[1,0,3,2] row_mask:0xf bank_mask:0xf bound_ctrl:1
	v_cndmask_b32_e64 v56, v67, v47, s[10:11]
	v_cndmask_b32_e64 v57, v47, v67, s[10:11]
	s_nop 1
	v_add_f32_dpp v50, v57, v56 quad_perm:[2,3,0,1] row_mask:0xf bank_mask:0xf bound_ctrl:1
	v_cndmask_b32_e64 v56, v65, v50, s[12:13]
	v_cndmask_b32_e64 v57, v50, v65, s[12:13]
	s_nop 1
	v_add_f32_dpp v49, v57, v56 row_shl:4 row_mask:0xf bank_mask:0x5
	s_nop 1
	v_add_f32_dpp v49, v57, v56 row_shr:4 row_mask:0xf bank_mask:0xa
	ds_read_b128 v[188:191], v124 offset:36608
	ds_read_b128 v[192:195], v124 offset:36864
	ds_read_b128 v[196:199], v124 offset:37120
	ds_read_b128 v[200:203], v124 offset:37376
	ds_read_b128 v[204:207], v124 offset:37632
	ds_read_b32 v208, v110 offset:37888
	v_add_f32_dpp v2, v2, v2 row_ror:4 row_mask:0xf bank_mask:0xf bound_ctrl:1
	s_nop 1
	v_add_f32_dpp v2, v2, v2 row_ror:8 row_mask:0xf bank_mask:0xf bound_ctrl:1
	v_pk_fma_f32 v[36:37], v[140:141], v[2:3], v[40:41] op_sel_hi:[1,0,1]
	v_pk_fma_f32 v[38:39], v[142:143], v[2:3], v[42:43] op_sel_hi:[1,0,1]
	s_waitcnt lgkmcnt(11)
	v_mul_f32_e32 v44, v36, v160
	v_mul_f32_e32 v52, v152, v36
	v_fmac_f32_e32 v44, v37, v161
	v_fmac_f32_e32 v52, v37, v153
	v_fmac_f32_e32 v44, v38, v162
	v_fmac_f32_e32 v52, v38, v154
	v_fmac_f32_e32 v44, v39, v163
	v_fmac_f32_e32 v52, v39, v155
	s_waitcnt lgkmcnt(6)
	v_pk_mul_f32 v[40:41], v[172:173], v[158:159] op_sel_hi:[1,0]
	v_pk_mul_f32 v[42:43], v[174:175], v[158:159] op_sel_hi:[1,0]
	v_add_f32_dpp v2, v44, v44 quad_perm:[1,0,3,2] row_mask:0xf bank_mask:0xf bound_ctrl:1
	v_pk_fma_f32 v[40:41], v[36:37], v[168:169], v[40:41]
	v_pk_fma_f32 v[42:43], v[38:39], v[170:171], v[42:43]
	v_add_f32_dpp v2, v2, v2 quad_perm:[2,3,0,1] row_mask:0xf bank_mask:0xf bound_ctrl:1
	ds_read_b128 v[136:139], v124 offset:38016
	ds_read_b128 v[140:143], v124 offset:38272
	ds_read_b128 v[144:147], v124 offset:38528
	ds_read_b128 v[148:151], v124 offset:38784
	ds_read_b128 v[152:155], v124 offset:39040
	ds_read_b32 v156, v110 offset:39296
	s_nop 1
	v_add_f32_dpp v2, v2, v2 row_ror:4 row_mask:0xf bank_mask:0xf bound_ctrl:1
	s_nop 1
	v_add_f32_dpp v2, v2, v2 row_ror:8 row_mask:0xf bank_mask:0xf bound_ctrl:1
	v_pk_fma_f32 v[36:37], v[164:165], v[2:3], v[40:41] op_sel_hi:[1,0,1]
	v_pk_fma_f32 v[38:39], v[166:167], v[2:3], v[42:43] op_sel_hi:[1,0,1]
	s_waitcnt lgkmcnt(11)
	v_mul_f32_e32 v44, v36, v188
	v_mul_f32_e32 v45, v176, v36
	v_fmac_f32_e32 v44, v37, v189
	v_fmac_f32_e32 v45, v37, v177
	v_fmac_f32_e32 v44, v38, v190
	v_fmac_f32_e32 v45, v38, v178
	v_fmac_f32_e32 v44, v39, v191
	v_fmac_f32_e32 v45, v39, v179
	s_waitcnt lgkmcnt(6)
	v_pk_mul_f32 v[40:41], v[200:201], v[208:209] op_sel_hi:[1,0]
	v_pk_mul_f32 v[42:43], v[202:203], v[208:209] op_sel_hi:[1,0]
	v_add_f32_dpp v2, v44, v44 quad_perm:[1,0,3,2] row_mask:0xf bank_mask:0xf bound_ctrl:1
	v_pk_fma_f32 v[40:41], v[36:37], v[196:197], v[40:41]
	v_pk_fma_f32 v[42:43], v[38:39], v[198:199], v[42:43]
	v_add_f32_dpp v2, v2, v2 quad_perm:[2,3,0,1] row_mask:0xf bank_mask:0xf bound_ctrl:1
	v_cndmask_b32_e64 v56, v52, v45, s[8:9]
	v_cndmask_b32_e64 v57, v45, v52, s[8:9]
	s_nop 1
	v_add_f32_dpp v53, v57, v56 quad_perm:[1,0,3,2] row_mask:0xf bank_mask:0xf bound_ctrl:1
	ds_read_b128 v[160:163], v124 offset:39424
	ds_read_b128 v[164:167], v124 offset:39680
	ds_read_b128 v[168:171], v124 offset:39936
	ds_read_b128 v[172:175], v124 offset:40192
	ds_read_b128 v[176:179], v124 offset:40448
	ds_read_b32 v158, v110 offset:40704
	v_add_f32_dpp v2, v2, v2 row_ror:4 row_mask:0xf bank_mask:0xf bound_ctrl:1
	s_nop 1
	v_add_f32_dpp v2, v2, v2 row_ror:8 row_mask:0xf bank_mask:0xf bound_ctrl:1
	v_pk_fma_f32 v[36:37], v[192:193], v[2:3], v[40:41] op_sel_hi:[1,0,1]
	v_pk_fma_f32 v[38:39], v[194:195], v[2:3], v[42:43] op_sel_hi:[1,0,1]
	s_waitcnt lgkmcnt(11)
; #define LAS __attribute__((address_space(3)))
; __device__ __forceinline__ float row16_sum(float x) { x += dpp_mov<0xB1>(x); x += dpp_mov<0x4E>(x); x += dpp_mov<0x124>(x); x += dpp_mov<0x128>(x); return x; }
; __device__ __forceinline__ void scan_phase(const KAS Args& a, LAS unsigned char* lds, int i, const int tid_, const int bid, const int nblk) {
;     ...
;                 for (int t = 0; t < TC; ++t) {
;                     f32x4 kk4n = kk4, nb4n = nb4, w4n = w4, k4n = k4, r4n = r4; float vn = v;
;                     if (t + 1 < TC) { const LAS float* sn = sb + (t + 1) * SST;
;                         kk4n = *(const LAS f32x4*)(sn); nb4n = *(const LAS f32x4*)(sn + 64); w4n = *(const LAS f32x4*)(sn + 128); k4n = *(const LAS f32x4*)(sn + 192); r4n = *(const LAS f32x4*)(sn + 256); vn = vb[(t + 1) * SST]; }
;                     __builtin_amdgcn_sched_barrier(0x6);
;                     float sa = fmaf(S[3], kk4[3], fmaf(S[2], kk4[2], fmaf(S[1], kk4[1], S[0] * kk4[0])));
;                     const f32x4 Tm = S * w4 + k4 * v;
;                     sa = row16_sum(sa);
;                     S = Tm + nb4 * sa;
;                     float y = fmaf(S[3], r4[3], fmaf(S[2], r4[2], fmaf(S[1], r4[1], S[0] * r4[0]))); y = row16_sum(y);
;                     ysel = (cgp == (t & 15)) ? y : ysel;
;                     if ((t & 15) == 15) yb[(t - 15 + cgp) * 32 + rl] = ysel;
;                     kk4 = kk4n; nb4 = nb4n; w4 = w4n; k4 = k4n; r4 = r4n; v = vn; }
	v_mul_f32_e32 v44, v36, v136
	v_mul_f32_e32 v61, v204, v36
	v_fmac_f32_e32 v44, v37, v137
	v_fmac_f32_e32 v61, v37, v205
	v_fmac_f32_e32 v44, v38, v138
	v_fmac_f32_e32 v61, v38, v206
	v_fmac_f32_e32 v44, v39, v139
	v_fmac_f32_e32 v61, v39, v207
	s_waitcnt lgkmcnt(6)
	v_pk_mul_f32 v[40:41], v[148:149], v[156:157] op_sel_hi:[1,0]
	v_pk_mul_f32 v[42:43], v[150:151], v[156:157] op_sel_hi:[1,0]
	v_add_f32_dpp v2, v44, v44 quad_perm:[1,0,3,2] row_mask:0xf bank_mask:0xf bound_ctrl:1
	v_pk_fma_f32 v[40:41], v[36:37], v[144:145], v[40:41]
	v_pk_fma_f32 v[42:43], v[38:39], v[146:147], v[42:43]
	v_add_f32_dpp v2, v2, v2 quad_perm:[2,3,0,1] row_mask:0xf bank_mask:0xf bound_ctrl:1
	ds_read_b128 v[188:191], v124 offset:40832
	ds_read_b128 v[192:195], v124 offset:41088
	ds_read_b128 v[196:199], v124 offset:41344
	ds_read_b128 v[200:203], v124 offset:41600
	ds_read_b128 v[204:207], v124 offset:41856
	ds_read_b32 v208, v110 offset:42112
	s_nop 1
	v_add_f32_dpp v2, v2, v2 row_ror:4 row_mask:0xf bank_mask:0xf bound_ctrl:1
	s_nop 1
	v_add_f32_dpp v2, v2, v2 row_ror:8 row_mask:0xf bank_mask:0xf bound_ctrl:1
	v_pk_fma_f32 v[36:37], v[140:141], v[2:3], v[40:41] op_sel_hi:[1,0,1]
	v_pk_fma_f32 v[38:39], v[142:143], v[2:3], v[42:43] op_sel_hi:[1,0,1]
	s_waitcnt lgkmcnt(11)
	v_mul_f32_e32 v44, v36, v160
	v_mul_f32_e32 v55, v152, v36
	v_fmac_f32_e32 v44, v37, v161
	v_fmac_f32_e32 v55, v37, v153
	v_fmac_f32_e32 v44, v38, v162
	v_fmac_f32_e32 v55, v38, v154
	v_fmac_f32_e32 v44, v39, v163
	v_fmac_f32_e32 v55, v39, v155
	s_waitcnt lgkmcnt(6)
	v_pk_mul_f32 v[40:41], v[172:173], v[158:159] op_sel_hi:[1,0]
	v_pk_mul_f32 v[42:43], v[174:175], v[158:159] op_sel_hi:[1,0]
	v_add_f32_dpp v2, v44, v44 quad_perm:[1,0,3,2] row_mask:0xf bank_mask:0xf bound_ctrl:1
	v_pk_fma_f32 v[40:41], v[36:37], v[168:169], v[40:41]
	v_pk_fma_f32 v[42:43], v[38:39], v[170:171], v[42:43]
	v_add_f32_dpp v2, v2, v2 quad_perm:[2,3,0,1] row_mask:0xf bank_mask:0xf bound_ctrl:1
	v_cndmask_b32_e64 v56, v61, v55, s[8:9]
	v_cndmask_b32_e64 v57, v55, v61, s[8:9]
	s_nop 1
	v_add_f32_dpp v58, v57, v56 quad_perm:[1,0,3,2] row_mask:0xf bank_mask:0xf bound_ctrl:1
	v_cndmask_b32_e64 v56, v53, v58, s[10:11]
	v_cndmask_b32_e64 v57, v58, v53, s[10:11]
	s_nop 1
	v_add_f32_dpp v54, v57, v56 quad_perm:[2,3,0,1] row_mask:0xf bank_mask:0xf bound_ctrl:1
	ds_read_b128 v[136:139], v124 offset:42240
	ds_read_b128 v[140:143], v124 offset:42496
	ds_read_b128 v[144:147], v124 offset:42752
	ds_read_b128 v[148:151], v124 offset:43008
	ds_read_b128 v[152:155], v124 offset:43264
	ds_read_b32 v156, v110 offset:43520
	v_add_f32_dpp v2, v2, v2 row_ror:4 row_mask:0xf bank_mask:0xf bound_ctrl:1
	s_nop 1
	v_add_f32_dpp v2, v2, v2 row_ror:8 row_mask:0xf bank_mask:0xf bound_ctrl:1
	v_pk_fma_f32 v[36:37], v[164:165], v[2:3], v[40:41] op_sel_hi:[1,0,1]
	v_pk_fma_f32 v[38:39], v[166:167], v[2:3], v[42:43] op_sel_hi:[1,0,1]
	s_waitcnt lgkmcnt(11)
	v_mul_f32_e32 v44, v36, v188
	v_mul_f32_e32 v59, v176, v36
	v_fmac_f32_e32 v44, v37, v189
	v_fmac_f32_e32 v59, v37, v177
	v_fmac_f32_e32 v44, v38, v190
	v_fmac_f32_e32 v59, v38, v178
	v_fmac_f32_e32 v44, v39, v191
	v_fmac_f32_e32 v59, v39, v179
	s_waitcnt lgkmcnt(6)
	v_pk_mul_f32 v[40:41], v[200:201], v[208:209] op_sel_hi:[1,0]
	v_pk_mul_f32 v[42:43], v[202:203], v[208:209] op_sel_hi:[1,0]
	v_add_f32_dpp v2, v44, v44 quad_perm:[1,0,3,2] row_mask:0xf bank_mask:0xf bound_ctrl:1
	v_pk_fma_f32 v[40:41], v[36:37], v[196:197], v[40:41]
	v_pk_fma_f32 v[42:43], v[38:39], v[198:199], v[42:43]
	v_add_f32_dpp v2, v2, v2 quad_perm:[2,3,0,1] row_mask:0xf bank_mask:0xf bound_ctrl:1
	ds_read_b128 v[160:163], v124 offset:43648
	ds_read_b128 v[164:167], v124 offset:43904
	ds_read_b128 v[168:171], v124 offset:44160
	ds_read_b128 v[172:175], v124 offset:44416
	ds_read_b128 v[176:179], v124 offset:44672
	ds_read_b32 v158, v110 offset:44928
	s_nop 1
	v_add_f32_dpp v2, v2, v2 row_ror:4 row_mask:0xf bank_mask:0xf bound_ctrl:1
	s_nop 1
	v_add_f32_dpp v2, v2, v2 row_ror:8 row_mask:0xf bank_mask:0xf bound_ctrl:1
	v_pk_fma_f32 v[36:37], v[192:193], v[2:3], v[40:41] op_sel_hi:[1,0,1]
	v_pk_fma_f32 v[38:39], v[194:195], v[2:3], v[42:43] op_sel_hi:[1,0,1]
	s_waitcnt lgkmcnt(11)
	v_mul_f32_e32 v44, v36, v136
	v_mul_f32_e32 v60, v204, v36
	v_fmac_f32_e32 v44, v37, v137
	v_fmac_f32_e32 v60, v37, v205
	v_fmac_f32_e32 v44, v38, v138
	v_fmac_f32_e32 v60, v38, v206
	v_fmac_f32_e32 v44, v39, v139
	v_fmac_f32_e32 v60, v39, v207
	s_waitcnt lgkmcnt(6)
	v_pk_mul_f32 v[40:41], v[148:149], v[156:157] op_sel_hi:[1,0]
	v_pk_mul_f32 v[42:43], v[150:151], v[156:157] op_sel_hi:[1,0]
	v_add_f32_dpp v2, v44, v44 quad_perm:[1,0,3,2] row_mask:0xf bank_mask:0xf bound_ctrl:1
	v_pk_fma_f32 v[40:41], v[36:37], v[144:145], v[40:41]
	v_pk_fma_f32 v[42:43], v[38:39], v[146:147], v[42:43]
	v_add_f32_dpp v2, v2, v2 quad_perm:[2,3,0,1] row_mask:0xf bank_mask:0xf bound_ctrl:1
	v_cndmask_b32_e64 v56, v59, v60, s[8:9]
	v_cndmask_b32_e64 v57, v60, v59, s[8:9]
	s_nop 1
	v_add_f32_dpp v62, v57, v56 quad_perm:[1,0,3,2] row_mask:0xf bank_mask:0xf bound_ctrl:1
	v_add_f32_dpp v2, v2, v2 row_ror:4 row_mask:0xf bank_mask:0xf bound_ctrl:1
	s_nop 1
	v_add_f32_dpp v2, v2, v2 row_ror:8 row_mask:0xf bank_mask:0xf bound_ctrl:1
	v_pk_fma_f32 v[36:37], v[140:141], v[2:3], v[40:41] op_sel_hi:[1,0,1]
	v_pk_fma_f32 v[38:39], v[142:143], v[2:3], v[42:43] op_sel_hi:[1,0,1]
	s_waitcnt lgkmcnt(5)
; #define LAS __attribute__((address_space(3)))
; __device__ __forceinline__ void scan_stage(const u32x2 (&pz)[8], LAS float* buf, float* RKB, size_t mrow0, int t0, int tid, int h, int half, ...
;     ...
;     up4(pz[0], zr); up4(pz[1], zk); up4(pz[2], zv); up4(pz[3], zrp); up4(pz[4], zkp); up4(pz[5], zvp); up4(pz[6], ew); up4(pz[7], ic);
;     f32x4 r, k2, v, kkv, w; float n2 = 0.f, rkb = 0.f;
; #pragma unroll
;     for (int e = 0; e < 4; ++e) { r[e] = zr[e] + (zrp[e] - zr[e]) * mu_r[e]; const float k = zk[e] + (zkp[e] - zk[e]) * mu_k[e]; v[e] = zv[e] + (zvp[e] - zv[e]) * mu_v[e];
;         kkv[e] = k * kkc[e]; n2 += kkv[e] * kkv[e]; k2[e] = k * (1.0f + (ic[e] - 1.0f) * kac[e]); w[e] = __builtin_amdgcn_exp2f(-1.4426950408889634f * ew[e]); rkb += r[e] * k2[e] * rkc[e]; }
;     n2 = row16_sum(n2); rkb = row16_sum(rkb);
;     const float inv = __builtin_amdgcn_rsqf(fmaxf(n2, 1e-24f));
;     const f32x4 kkn = kkv * inv; f32x4 nb;
; #pragma unroll
;     for (int e = 0; e < 4; ++e) nb[e] = -kkn[e] * ic[e];
;     if (half == 0 && cgp == 0) RKB[(mrow0 + t0 + tl) * 8 + h] = rkb;
; __device__ __forceinline__ void scan_phase(const KAS Args& a, LAS unsigned char* lds, int i, const int tid_, const int bid, const int nblk) {
;     ...
;                 for (int t = 0; t < TC; ++t) {
;                     f32x4 kk4n = kk4, nb4n = nb4, w4n = w4, k4n = k4, r4n = r4; float vn = v;
;                     if (t + 1 < TC) { const LAS float* sn = sb + (t + 1) * SST;
;                         kk4n = *(const LAS f32x4*)(sn); nb4n = *(const LAS f32x4*)(sn + 64); w4n = *(const LAS f32x4*)(sn + 128); k4n = *(const LAS f32x4*)(sn + 192); r4n = *(const LAS f32x4*)(sn + 256); vn = vb[(t + 1) * SST]; }
;                     __builtin_amdgcn_sched_barrier(0x6);
;                     float sa = fmaf(S[3], kk4[3], fmaf(S[2], kk4[2], fmaf(S[1], kk4[1], S[0] * kk4[0])));
;                     const f32x4 Tm = S * w4 + k4 * v;
;                     sa = row16_sum(sa);
;                     S = Tm + nb4 * sa;
;                     float y = fmaf(S[3], r4[3], fmaf(S[2], r4[2], fmaf(S[1], r4[1], S[0] * r4[0]))); y = row16_sum(y);
;                     ysel = (cgp == (t & 15)) ? y : ysel;
;                     if ((t & 15) == 15) yb[(t - 15 + cgp) * 32 + rl] = ysel;
;                     kk4 = kk4n; nb4 = nb4n; w4 = w4n; k4 = k4n; r4 = r4n; v = vn; }
	v_mul_f32_e32 v44, v36, v160
	v_mul_f32_e32 v51, v152, v36
	v_fmac_f32_e32 v44, v37, v161
	v_fmac_f32_e32 v51, v37, v153
	v_fmac_f32_e32 v44, v38, v162
	v_fmac_f32_e32 v51, v38, v154
	v_fmac_f32_e32 v44, v39, v163
	v_fmac_f32_e32 v51, v39, v155
	s_waitcnt lgkmcnt(0)
	v_pk_mul_f32 v[40:41], v[172:173], v[158:159] op_sel_hi:[1,0]
	v_pk_mul_f32 v[42:43], v[174:175], v[158:159] op_sel_hi:[1,0]
	v_add_f32_dpp v2, v44, v44 quad_perm:[1,0,3,2] row_mask:0xf bank_mask:0xf bound_ctrl:1
	v_pk_fma_f32 v[40:41], v[36:37], v[168:169], v[40:41]
	v_pk_fma_f32 v[42:43], v[38:39], v[170:171], v[42:43]
	v_add_f32_dpp v2, v2, v2 quad_perm:[2,3,0,1] row_mask:0xf bank_mask:0xf bound_ctrl:1
	s_nop 1
	v_add_f32_dpp v2, v2, v2 row_ror:4 row_mask:0xf bank_mask:0xf bound_ctrl:1
	s_nop 1
	v_add_f32_dpp v2, v2, v2 row_ror:8 row_mask:0xf bank_mask:0xf bound_ctrl:1
	v_pk_fma_f32 v[36:37], v[164:165], v[2:3], v[40:41] op_sel_hi:[1,0,1]
	v_pk_fma_f32 v[38:39], v[166:167], v[2:3], v[42:43] op_sel_hi:[1,0,1]
	v_mul_f32_e32 v63, v176, v36
	v_fmac_f32_e32 v63, v37, v177
	v_fmac_f32_e32 v63, v38, v178
	v_fmac_f32_e32 v63, v39, v179
	v_cndmask_b32_e64 v56, v51, v63, s[8:9]
	v_cndmask_b32_e64 v57, v63, v51, s[8:9]
	s_nop 1
	v_add_f32_dpp v66, v57, v56 quad_perm:[1,0,3,2] row_mask:0xf bank_mask:0xf bound_ctrl:1
	v_cndmask_b32_e64 v56, v62, v66, s[10:11]
	v_cndmask_b32_e64 v57, v66, v62, s[10:11]
	s_nop 1
	v_add_f32_dpp v64, v57, v56 quad_perm:[2,3,0,1] row_mask:0xf bank_mask:0xf bound_ctrl:1
	v_cndmask_b32_e64 v56, v54, v64, s[12:13]
	v_cndmask_b32_e64 v57, v64, v54, s[12:13]
	s_nop 1
	v_add_f32_dpp v46, v57, v56 row_shl:4 row_mask:0xf bank_mask:0x5
	s_nop 1
	v_add_f32_dpp v46, v57, v56 row_shr:4 row_mask:0xf bank_mask:0xa
	v_cndmask_b32_e64 v56, v49, v46, s[14:15]
	v_cndmask_b32_e64 v57, v46, v49, s[14:15]
	s_nop 1
	v_add_f32_dpp v48, v57, v56 row_ror:8 row_mask:0xf bank_mask:0xf bound_ctrl:1
	ds_write_b32 v122, v48 offset:2048
	s_cbranch_vccnz .LBB0_183
	s_waitcnt vmcnt(4)
	v_lshlrev_b32_e32 v28, 16, v80
	v_and_b32_e32 v29, 0xffff0000, v80
	v_lshlrev_b32_e32 v30, 16, v86
	v_and_b32_e32 v31, 0xffff0000, v86
	v_pk_add_f32 v[30:31], v[30:31], v[28:29] neg_lo:[0,1] neg_hi:[0,1]
	s_waitcnt vmcnt(3)
	v_lshlrev_b32_e32 v32, 16, v88
	v_pk_fma_f32 v[28:29], v[16:17], v[30:31], v[28:29]
	v_lshlrev_b32_e32 v30, 16, v82
	v_and_b32_e32 v31, 0xffff0000, v82
	v_and_b32_e32 v33, 0xffff0000, v88
	s_waitcnt vmcnt(0)
	v_lshlrev_b32_e32 v40, 16, v94
	v_and_b32_e32 v41, 0xffff0000, v94
	v_pk_add_f32 v[32:33], v[32:33], v[30:31] neg_lo:[0,1] neg_hi:[0,1]
	v_lshlrev_b32_e32 v46, 16, v89
	v_pk_fma_f32 v[30:31], v[20:21], v[32:33], v[30:31]
	v_pk_add_f32 v[32:33], v[40:41], -1.0 op_sel_hi:[1,0]
	v_pk_mul_f32 v[42:43], v[12:13], v[30:31]
	v_pk_fma_f32 v[32:33], v[24:25], v[32:33], 1.0 op_sel_hi:[1,1,0]
	v_and_b32_e32 v47, 0xffff0000, v89
	v_pk_mul_f32 v[32:33], v[30:31], v[32:33]
	v_lshlrev_b32_e32 v30, 16, v81
	v_pk_mul_f32 v[34:35], v[28:29], v[32:33]
	v_and_b32_e32 v31, 0xffff0000, v81
	v_fma_f32 v54, v4, v34, 0
	v_fmac_f32_e32 v54, v5, v35
	v_lshlrev_b32_e32 v34, 16, v87
	v_and_b32_e32 v35, 0xffff0000, v87
	v_pk_add_f32 v[34:35], v[34:35], v[30:31] neg_lo:[0,1] neg_hi:[0,1]
	v_lshlrev_b32_e32 v44, 16, v95
	v_pk_fma_f32 v[30:31], v[18:19], v[34:35], v[30:31]
	v_lshlrev_b32_e32 v34, 16, v83
	v_and_b32_e32 v35, 0xffff0000, v83
	v_and_b32_e32 v45, 0xffff0000, v95
	v_pk_add_f32 v[46:47], v[46:47], v[34:35] neg_lo:[0,1] neg_hi:[0,1]
	v_pk_mul_f32 v[48:49], v[42:43], v[42:43]
	v_pk_fma_f32 v[46:47], v[22:23], v[46:47], v[34:35]
	v_pk_add_f32 v[34:35], v[44:45], -1.0 op_sel_hi:[1,0]
	v_add_f32_e32 v2, v48, v49
	v_pk_fma_f32 v[34:35], v[26:27], v[34:35], 1.0 op_sel_hi:[1,1,0]
	v_mov_b32_e32 v48, 0
	v_pk_mul_f32 v[34:35], v[46:47], v[34:35]
	v_pk_mul_f32 v[46:47], v[14:15], v[46:47]
	v_pk_mul_f32 v[50:51], v[30:31], v[34:35]
	v_pk_mul_f32 v[52:53], v[46:47], v[46:47]
	v_fmac_f32_e32 v54, v6, v50
	v_add_f32_e32 v2, v52, v2
	v_add_f32_e32 v2, v53, v2
	v_fmac_f32_e32 v54, v7, v51
	v_mov_b32_e32 v50, 0
	v_add_f32_dpp v2, v2, v2 quad_perm:[1,0,3,2] row_mask:0xf bank_mask:0xf bound_ctrl:1
	v_add_f32_dpp v49, v54, v54 quad_perm:[1,0,3,2] row_mask:0xf bank_mask:0xf bound_ctrl:1
	s_nop 0
	v_add_f32_dpp v2, v2, v2 quad_perm:[2,3,0,1] row_mask:0xf bank_mask:0xf bound_ctrl:1
	v_add_f32_dpp v49, v49, v49 quad_perm:[2,3,0,1] row_mask:0xf bank_mask:0xf bound_ctrl:1
	s_nop 0
	v_add_f32_dpp v2, v2, v2 row_ror:4 row_mask:0xf bank_mask:0xf bound_ctrl:1
	v_add_f32_dpp v49, v49, v49 row_ror:4 row_mask:0xf bank_mask:0xf bound_ctrl:1
	s_nop 0
	v_mov_b32_dpp v48, v2 row_ror:8 row_mask:0xf bank_mask:0xf
	v_mov_b32_dpp v50, v49 row_ror:8 row_mask:0xf bank_mask:0xf
	s_and_saveexec_b64 s[2:3], s[42:43]
	s_cbranch_execz .LBB0_193
	v_lshl_add_u64 v[52:53], s[88:89], 0, v[100:101]
	v_add_f32_e32 v49, v49, v50
	global_store_dword v[52:53], v49, off
